# P13: lean loop takes all 16 prompt rows + the sample row of a wave; rows_res<5> tail not run
# speedup vs baseline: 1.0015x; 1.0000x over previous
;     __device__ __forceinline__ const float* in(int i) const { return karg_in(i); }
; __device__ __forceinline__ const float* xrow_ptr(const Ctx& C, int row) { return row < MPROMPT ? C.in(0) + (size_t)row * DM : C.in(1) + (size_t)(row - MPROMPT) * DM; }
; __device__ __forceinline__ v4f ld4_bf16(const bf16* p) { const v2u w = *(const v2u*)p; return (v4f){bf_lo(w.x), bf_hi(w.x), bf_lo(w.y), bf_hi(w.y)}; }
; __device__ __forceinline__ float ssq4(v4f v) { return (v.x * v.x + v.y * v.y) + (v.z * v.z + v.w * v.w); }
; #define FTID const int ftid_ = fresh_tid()
; template <int R, bool BASE_F32, bool OUT_F32>
; __device__ __forceinline__ void rows_res(const Ctx& C, int m0, int stride, int mx, const float* gpost, float scale, int lane) {
;     ...
;     for (int r = 0; r < R; ++r) { mr[r] = (r == 4) ? mx : m0 + r * stride; ok[r] = (r == 4) ? (mx < M) : (mr[r] < MPROMPT); const int mm = ok[r] ? mr[r] : 0;
; #pragma unroll
;         for (int j = 0; j < 4; ++j) d[r][j] = ld4_bf16(D + (size_t)mm * DM + 4 * lane + 256 * j);
;         if (BASE_F32) { const float* x = xrow_ptr(C, mm);
; #pragma unroll
;             for (int j = 0; j < 4; ++j) b[r][j] = ld4_f32(x + 4 * lane + 256 * j);
;         } else { const float inv = C.RS()[mm];
; #pragma unroll
;             for (int j = 0; j < 4; ++j) b[r][j] = ld4_bf16(XN + (size_t)mm * DM + 4 * lane + 256 * j) * inv;
;         } }
; #pragma unroll
;     for (int r = 0; r < R; ++r) { float s = 0.f;
; #pragma unroll
;         for (int j = 0; j < 4; ++j) s += ssq4(d[r][j]);
;         r1[r] = s; }
; __global__ void __launch_bounds__(NTHREADS, 2) fwd_kernel(Args args) {
;     ...
;     { FTID; const float* gp = C.in(32); { const int gw_ = GWV, ngw_ = NGWV, nit = (MPROMPT + 4 * ngw_ - 1) / (4 * ngw_);
;       for (int it = 0; it < nit - 1; ++it) rows_res<4, false, true>(C, gw_ + 4 * it * ngw_, ngw_, M, gp, 0.5f, LANE);
.LBB0_1272:
	s_or_b64 exec, exec, s[4:5]
	s_mov_b64 s[0:1], s[80:81]
	s_waitcnt lgkmcnt(0)
	s_barrier
	s_load_dwordx2 s[8:9], s[0:1], 0x100
	v_readfirstlane_b32 s0, v182
	v_lshlrev_b32_e32 v0, 2, v182
	s_ashr_i32 s26, s0, 6
	v_readlane_b32 s0, v232, 0
	v_and_b32_e32 v0, 0xfc, v0
	s_add_i32 s15, s26, s0
	v_mov_b32_e32 v17, 0
	s_and_b64 vcc, exec, s[6:7]
	v_lshlrev_b32_e32 v16, 2, v0
	v_lshlrev_b32_e32 v18, 1, v0
	s_load_dwordx2 s[98:99], s[80:81], 0x110
	s_load_dwordx2 s[100:101], s[80:81], 0x100
	v_and_b32_e32 v176, 63, v182
	v_lshlrev_b32_e32 v170, 3, v176
	s_lshl_b32 vcc_lo, s15, 11
	v_add_u32_e32 v170, vcc_lo, v170
	v_add_u32_e32 v171, 0x3000000, v170
	v_add_u32_e32 v170, 0x7100000, v170
	v_mov_b32_e32 v173, v171
	s_lshl_b32 vcc_lo, s15, 2
	v_mov_b32_e32 v172, 0x2a80000
	v_add_u32_e32 v172, vcc_lo, v172
	v_mov_b32_e32 v174, v172
	s_lshl_b32 vcc_lo, s15, 12
	v_lshlrev_b32_e32 v175, 4, v176
	v_add_u32_e32 v175, vcc_lo, v175
	v_lshlrev_b32_e32 v176, 4, v176
	v_mov_b32_e32 v138, 0x358637bd
	s_waitcnt lgkmcnt(0)
	global_load_dwordx4 v[192:195], v176, s[100:101]
	global_load_dwordx4 v[196:199], v176, s[100:101] offset:1024
	global_load_dwordx4 v[200:203], v176, s[100:101] offset:2048
	global_load_dwordx4 v[204:207], v176, s[100:101] offset:3072
	s_load_dwordx2 s[100:101], s[80:81], 0x108
	global_load_dword v52, v172, s[98:99]
	global_load_dwordx2 v[20:21], v170, s[98:99]
	global_load_dwordx2 v[22:23], v170, s[98:99] offset:512
	global_load_dwordx2 v[24:25], v170, s[98:99] offset:1024
	global_load_dwordx2 v[26:27], v170, s[98:99] offset:1536
	global_load_dwordx2 v[36:37], v171, s[98:99]
	global_load_dwordx2 v[38:39], v171, s[98:99] offset:512
	global_load_dwordx2 v[40:41], v171, s[98:99] offset:1024
	global_load_dwordx2 v[42:43], v171, s[98:99] offset:1536
	v_add_u32_e32 v170, 0x400000, v170
	v_add_u32_e32 v171, 0x400000, v171
	v_add_u32_e32 v172, 0x2000, v172
	global_load_dword v54, v172, s[98:99]
	global_load_dwordx2 v[28:29], v170, s[98:99]
	global_load_dwordx2 v[30:31], v170, s[98:99] offset:512
	global_load_dwordx2 v[32:33], v170, s[98:99] offset:1024
	global_load_dwordx2 v[34:35], v170, s[98:99] offset:1536
	global_load_dwordx2 v[44:45], v171, s[98:99]
	global_load_dwordx2 v[46:47], v171, s[98:99] offset:512
	global_load_dwordx2 v[48:49], v171, s[98:99] offset:1024
	global_load_dwordx2 v[50:51], v171, s[98:99] offset:1536
	v_add_u32_e32 v170, 0x400000, v170
	v_add_u32_e32 v171, 0x400000, v171
	v_add_u32_e32 v172, 0x2000, v172
	global_load_dword v88, v172, s[98:99]
	global_load_dwordx2 v[56:57], v170, s[98:99]
	global_load_dwordx2 v[58:59], v170, s[98:99] offset:512
	global_load_dwordx2 v[60:61], v170, s[98:99] offset:1024
	global_load_dwordx2 v[62:63], v170, s[98:99] offset:1536
	global_load_dwordx2 v[72:73], v171, s[98:99]
	global_load_dwordx2 v[74:75], v171, s[98:99] offset:512
	global_load_dwordx2 v[76:77], v171, s[98:99] offset:1024
	global_load_dwordx2 v[78:79], v171, s[98:99] offset:1536
	v_add_u32_e32 v170, 0x400000, v170
	v_add_u32_e32 v171, 0x400000, v171
	v_add_u32_e32 v172, 0x2000, v172
	global_load_dword v90, v172, s[98:99]
	global_load_dwordx2 v[64:65], v170, s[98:99]
	global_load_dwordx2 v[66:67], v170, s[98:99] offset:512
	global_load_dwordx2 v[68:69], v170, s[98:99] offset:1024
	global_load_dwordx2 v[70:71], v170, s[98:99] offset:1536
	global_load_dwordx2 v[80:81], v171, s[98:99]
	global_load_dwordx2 v[82:83], v171, s[98:99] offset:512
	global_load_dwordx2 v[84:85], v171, s[98:99] offset:1024
	global_load_dwordx2 v[86:87], v171, s[98:99] offset:1536
	v_add_u32_e32 v170, 0x400000, v170
	v_add_u32_e32 v171, 0x400000, v171
	v_add_u32_e32 v172, 0x2000, v172
	s_waitcnt vmcnt(31)
	v_lshlrev_b32_e32 v96, 16, v20
	v_and_b32_e32 v97, 0xffff0000, v20
	v_lshlrev_b32_e32 v98, 16, v21
	v_and_b32_e32 v99, 0xffff0000, v21
	v_lshlrev_b32_e32 v100, 16, v22
	v_and_b32_e32 v101, 0xffff0000, v22
	v_lshlrev_b32_e32 v102, 16, v23
	v_and_b32_e32 v103, 0xffff0000, v23
	v_lshlrev_b32_e32 v104, 16, v24
	v_and_b32_e32 v105, 0xffff0000, v24
	v_lshlrev_b32_e32 v106, 16, v25
	v_and_b32_e32 v107, 0xffff0000, v25
	v_lshlrev_b32_e32 v108, 16, v26
	v_and_b32_e32 v109, 0xffff0000, v26
	v_lshlrev_b32_e32 v110, 16, v27
	v_and_b32_e32 v111, 0xffff0000, v27
	v_pk_mul_f32 v[128:129], v[96:97], v[96:97]
	v_pk_fma_f32 v[128:129], v[98:99], v[98:99], v[128:129]
	v_pk_fma_f32 v[128:129], v[100:101], v[100:101], v[128:129]
	v_pk_fma_f32 v[128:129], v[102:103], v[102:103], v[128:129]
	v_pk_fma_f32 v[128:129], v[104:105], v[104:105], v[128:129]
	v_pk_fma_f32 v[128:129], v[106:107], v[106:107], v[128:129]
	v_pk_fma_f32 v[128:129], v[108:109], v[108:109], v[128:129]
	v_pk_fma_f32 v[128:129], v[110:111], v[110:111], v[128:129]
	s_nop 0
	v_add_f32_e32 v128, v128, v129
	s_waitcnt vmcnt(22)
;     __device__ __forceinline__ float* out() const { return (float*)karg_in(33); }
; __device__ __forceinline__ float ssq4(v4f v) { return (v.x * v.x + v.y * v.y) + (v.z * v.z + v.w * v.w); }
; template <int R, bool BASE_F32, bool OUT_F32>
; __device__ __forceinline__ void rows_res(const Ctx& C, int m0, int stride, int mx, const float* gpost, float scale, int lane) {
;     ...
;     for (int r = 0; r < R; ++r) { float s = 0.f;
; #pragma unroll
;         for (int j = 0; j < 4; ++j) s += ssq4(d[r][j]);
;         r1[r] = s; }
; #pragma unroll
;     for (int r = 0; r < R; ++r) r1[r] = rsqrtf(wave_sum(r1[r]) * (1.f / DM) + EPS) * scale;
; #pragma unroll
;     for (int j = 0; j < 4; ++j) { const v4f gp = ld4_f32(gpost + 4 * lane + 256 * j);
; #pragma unroll
;         for (int r = 0; r < R; ++r) d[r][j] = b[r][j] + d[r][j] * r1[r] * gp; }
;     if (OUT_F32) { float* Y = C.out();
; #pragma unroll
;         for (int r = 0; r < R; ++r)
; #pragma unroll
;             for (int j = 0; j < 4; ++j) if (ok[r]) *(v4f*)(Y + (size_t)mr[r] * DM + 4 * lane + 256 * j) = d[r][j];
	v_lshlrev_b32_e32 v112, 16, v28
	v_and_b32_e32 v113, 0xffff0000, v28
	v_lshlrev_b32_e32 v114, 16, v29
	v_and_b32_e32 v115, 0xffff0000, v29
	v_lshlrev_b32_e32 v116, 16, v30
	v_and_b32_e32 v117, 0xffff0000, v30
	v_lshlrev_b32_e32 v118, 16, v31
	v_and_b32_e32 v119, 0xffff0000, v31
	v_lshlrev_b32_e32 v120, 16, v32
	v_and_b32_e32 v121, 0xffff0000, v32
	v_lshlrev_b32_e32 v122, 16, v33
	v_and_b32_e32 v123, 0xffff0000, v33
	v_lshlrev_b32_e32 v124, 16, v34
	v_and_b32_e32 v125, 0xffff0000, v34
	v_lshlrev_b32_e32 v126, 16, v35
	v_and_b32_e32 v127, 0xffff0000, v35
	v_pk_mul_f32 v[130:131], v[112:113], v[112:113]
	v_pk_fma_f32 v[130:131], v[114:115], v[114:115], v[130:131]
	v_pk_fma_f32 v[130:131], v[116:117], v[116:117], v[130:131]
	v_pk_fma_f32 v[130:131], v[118:119], v[118:119], v[130:131]
	v_pk_fma_f32 v[130:131], v[120:121], v[120:121], v[130:131]
	v_pk_fma_f32 v[130:131], v[122:123], v[122:123], v[130:131]
	v_pk_fma_f32 v[130:131], v[124:125], v[124:125], v[130:131]
	v_pk_fma_f32 v[130:131], v[126:127], v[126:127], v[130:131]
	s_nop 0
	v_add_f32_e32 v130, v130, v131
	s_nop 1
	v_add_f32_dpp v128, v128, v128 quad_perm:[1,0,3,2] row_mask:0xf bank_mask:0xf
	v_add_f32_dpp v130, v130, v130 quad_perm:[1,0,3,2] row_mask:0xf bank_mask:0xf
	s_nop 0
	v_add_f32_dpp v128, v128, v128 quad_perm:[2,3,0,1] row_mask:0xf bank_mask:0xf
	v_add_f32_dpp v130, v130, v130 quad_perm:[2,3,0,1] row_mask:0xf bank_mask:0xf
	s_nop 0
	v_add_f32_dpp v128, v128, v128 row_half_mirror row_mask:0xf bank_mask:0xf
	v_add_f32_dpp v130, v130, v130 row_half_mirror row_mask:0xf bank_mask:0xf
	s_nop 0
	v_add_f32_dpp v128, v128, v128 row_mirror row_mask:0xf bank_mask:0xf
	v_add_f32_dpp v130, v130, v130 row_mirror row_mask:0xf bank_mask:0xf
	s_nop 0
	ds_bpermute_b32 v136, v187, v128
	ds_bpermute_b32 v137, v187, v130
	s_waitcnt lgkmcnt(0)
	v_add_f32_e32 v128, v128, v136
	v_add_f32_e32 v130, v130, v137
	ds_bpermute_b32 v136, v188, v128
	ds_bpermute_b32 v137, v188, v130
	s_waitcnt lgkmcnt(0)
	v_add_f32_e32 v128, v128, v136
	v_add_f32_e32 v130, v130, v137
	v_fmamk_f32 v128, v128, 0x3a800000, v138
	v_fmamk_f32 v130, v130, 0x3a800000, v138
	s_nop 0
	v_rsq_f32_e32 v128, v128
	v_rsq_f32_e32 v130, v130
	s_nop 1
	v_mul_f32_e32 v128, 0.5, v128
	v_mul_f32_e32 v130, 0.5, v130
	s_waitcnt vmcnt(18)
	v_pk_mul_f32 v[96:97], v[128:129], v[96:97] op_sel_hi:[0,1]
	v_pk_mul_f32 v[98:99], v[128:129], v[98:99] op_sel_hi:[0,1]
	v_pk_mul_f32 v[100:101], v[128:129], v[100:101] op_sel_hi:[0,1]
	v_pk_mul_f32 v[102:103], v[128:129], v[102:103] op_sel_hi:[0,1]
	v_pk_mul_f32 v[104:105], v[128:129], v[104:105] op_sel_hi:[0,1]
	v_pk_mul_f32 v[106:107], v[128:129], v[106:107] op_sel_hi:[0,1]
	v_pk_mul_f32 v[108:109], v[128:129], v[108:109] op_sel_hi:[0,1]
	v_pk_mul_f32 v[110:111], v[128:129], v[110:111] op_sel_hi:[0,1]
	v_pk_mul_f32 v[96:97], v[96:97], v[192:193]
	v_pk_mul_f32 v[98:99], v[98:99], v[194:195]
	v_pk_mul_f32 v[100:101], v[100:101], v[196:197]
	v_pk_mul_f32 v[102:103], v[102:103], v[198:199]
	v_pk_mul_f32 v[104:105], v[104:105], v[200:201]
	v_pk_mul_f32 v[106:107], v[106:107], v[202:203]
	v_pk_mul_f32 v[108:109], v[108:109], v[204:205]
	v_pk_mul_f32 v[110:111], v[110:111], v[206:207]
	v_lshlrev_b32_e32 v20, 16, v36
	v_and_b32_e32 v21, 0xffff0000, v36
	v_lshlrev_b32_e32 v22, 16, v37
	v_and_b32_e32 v23, 0xffff0000, v37
	v_lshlrev_b32_e32 v24, 16, v38
	v_and_b32_e32 v25, 0xffff0000, v38
	v_lshlrev_b32_e32 v26, 16, v39
	v_and_b32_e32 v27, 0xffff0000, v39
	v_pk_fma_f32 v[96:97], v[52:53], v[20:21], v[96:97] op_sel_hi:[0,1,1]
	v_pk_fma_f32 v[98:99], v[52:53], v[22:23], v[98:99] op_sel_hi:[0,1,1]
	v_pk_fma_f32 v[100:101], v[52:53], v[24:25], v[100:101] op_sel_hi:[0,1,1]
	v_pk_fma_f32 v[102:103], v[52:53], v[26:27], v[102:103] op_sel_hi:[0,1,1]
	v_lshlrev_b32_e32 v20, 16, v40
	v_and_b32_e32 v21, 0xffff0000, v40
	v_lshlrev_b32_e32 v22, 16, v41
	v_and_b32_e32 v23, 0xffff0000, v41
	v_lshlrev_b32_e32 v24, 16, v42
	v_and_b32_e32 v25, 0xffff0000, v42
	v_lshlrev_b32_e32 v26, 16, v43
	v_and_b32_e32 v27, 0xffff0000, v43
	v_pk_fma_f32 v[104:105], v[52:53], v[20:21], v[104:105] op_sel_hi:[0,1,1]
	v_pk_fma_f32 v[106:107], v[52:53], v[22:23], v[106:107] op_sel_hi:[0,1,1]
	v_pk_fma_f32 v[108:109], v[52:53], v[24:25], v[108:109] op_sel_hi:[0,1,1]
	v_pk_fma_f32 v[110:111], v[52:53], v[26:27], v[110:111] op_sel_hi:[0,1,1]
	global_store_dwordx4 v175, v[96:99], s[100:101]
	global_store_dwordx4 v175, v[100:103], s[100:101] offset:1024
	global_store_dwordx4 v175, v[104:107], s[100:101] offset:2048
	global_store_dwordx4 v175, v[108:111], s[100:101] offset:3072
	v_add_u32_e32 v175, 0x800000, v175
	v_pk_mul_f32 v[112:113], v[130:131], v[112:113] op_sel_hi:[0,1]
	v_pk_mul_f32 v[114:115], v[130:131], v[114:115] op_sel_hi:[0,1]
	v_pk_mul_f32 v[116:117], v[130:131], v[116:117] op_sel_hi:[0,1]
	v_pk_mul_f32 v[118:119], v[130:131], v[118:119] op_sel_hi:[0,1]
	v_pk_mul_f32 v[120:121], v[130:131], v[120:121] op_sel_hi:[0,1]
	v_pk_mul_f32 v[122:123], v[130:131], v[122:123] op_sel_hi:[0,1]
	v_pk_mul_f32 v[124:125], v[130:131], v[124:125] op_sel_hi:[0,1]
	v_pk_mul_f32 v[126:127], v[130:131], v[126:127] op_sel_hi:[0,1]
	v_pk_mul_f32 v[112:113], v[112:113], v[192:193]
	v_pk_mul_f32 v[114:115], v[114:115], v[194:195]
	v_pk_mul_f32 v[116:117], v[116:117], v[196:197]
	v_pk_mul_f32 v[118:119], v[118:119], v[198:199]
	v_pk_mul_f32 v[120:121], v[120:121], v[200:201]
	v_pk_mul_f32 v[122:123], v[122:123], v[202:203]
	v_pk_mul_f32 v[124:125], v[124:125], v[204:205]
	v_pk_mul_f32 v[126:127], v[126:127], v[206:207]
	v_lshlrev_b32_e32 v28, 16, v44
	v_and_b32_e32 v29, 0xffff0000, v44
	v_lshlrev_b32_e32 v30, 16, v45
	v_and_b32_e32 v31, 0xffff0000, v45
;     __device__ __forceinline__ float* out() const { return (float*)karg_in(33); }
; __device__ __forceinline__ const float* xrow_ptr(const Ctx& C, int row) { return row < MPROMPT ? C.in(0) + (size_t)row * DM : C.in(1) + (size_t)(row - MPROMPT) * DM; }
; __device__ __forceinline__ v4f ld4_bf16(const bf16* p) { const v2u w = *(const v2u*)p; return (v4f){bf_lo(w.x), bf_hi(w.x), bf_lo(w.y), bf_hi(w.y)}; }
; __device__ __forceinline__ float ssq4(v4f v) { return (v.x * v.x + v.y * v.y) + (v.z * v.z + v.w * v.w); }
; template <int R, bool BASE_F32, bool OUT_F32>
; __device__ __forceinline__ void rows_res(const Ctx& C, int m0, int stride, int mx, const float* gpost, float scale, int lane) {
;     ...
;     for (int r = 0; r < R; ++r) { mr[r] = (r == 4) ? mx : m0 + r * stride; ok[r] = (r == 4) ? (mx < M) : (mr[r] < MPROMPT); const int mm = ok[r] ? mr[r] : 0;
; #pragma unroll
;         for (int j = 0; j < 4; ++j) d[r][j] = ld4_bf16(D + (size_t)mm * DM + 4 * lane + 256 * j);
;         if (BASE_F32) { const float* x = xrow_ptr(C, mm);
; #pragma unroll
;             for (int j = 0; j < 4; ++j) b[r][j] = ld4_f32(x + 4 * lane + 256 * j);
;         } else { const float inv = C.RS()[mm];
; #pragma unroll
;             for (int j = 0; j < 4; ++j) b[r][j] = ld4_bf16(XN + (size_t)mm * DM + 4 * lane + 256 * j) * inv;
;         } }
; #pragma unroll
;     for (int r = 0; r < R; ++r) { float s = 0.f;
; #pragma unroll
;         for (int j = 0; j < 4; ++j) s += ssq4(d[r][j]);
;         r1[r] = s; }
; #pragma unroll
;     for (int r = 0; r < R; ++r) r1[r] = rsqrtf(wave_sum(r1[r]) * (1.f / DM) + EPS) * scale;
; #pragma unroll
;     for (int j = 0; j < 4; ++j) { const v4f gp = ld4_f32(gpost + 4 * lane + 256 * j);
; #pragma unroll
;         for (int r = 0; r < R; ++r) d[r][j] = b[r][j] + d[r][j] * r1[r] * gp; }
;     if (OUT_F32) { float* Y = C.out();
; #pragma unroll
;         for (int r = 0; r < R; ++r)
; #pragma unroll
;             for (int j = 0; j < 4; ++j) if (ok[r]) *(v4f*)(Y + (size_t)mr[r] * DM + 4 * lane + 256 * j) = d[r][j];
	v_lshlrev_b32_e32 v32, 16, v46
	v_and_b32_e32 v33, 0xffff0000, v46
	v_lshlrev_b32_e32 v34, 16, v47
	v_and_b32_e32 v35, 0xffff0000, v47
	v_pk_fma_f32 v[112:113], v[54:55], v[28:29], v[112:113] op_sel_hi:[0,1,1]
	v_pk_fma_f32 v[114:115], v[54:55], v[30:31], v[114:115] op_sel_hi:[0,1,1]
	v_pk_fma_f32 v[116:117], v[54:55], v[32:33], v[116:117] op_sel_hi:[0,1,1]
	v_pk_fma_f32 v[118:119], v[54:55], v[34:35], v[118:119] op_sel_hi:[0,1,1]
	v_lshlrev_b32_e32 v28, 16, v48
	v_and_b32_e32 v29, 0xffff0000, v48
	v_lshlrev_b32_e32 v30, 16, v49
	v_and_b32_e32 v31, 0xffff0000, v49
	v_lshlrev_b32_e32 v32, 16, v50
	v_and_b32_e32 v33, 0xffff0000, v50
	v_lshlrev_b32_e32 v34, 16, v51
	v_and_b32_e32 v35, 0xffff0000, v51
	v_pk_fma_f32 v[120:121], v[54:55], v[28:29], v[120:121] op_sel_hi:[0,1,1]
	v_pk_fma_f32 v[122:123], v[54:55], v[30:31], v[122:123] op_sel_hi:[0,1,1]
	v_pk_fma_f32 v[124:125], v[54:55], v[32:33], v[124:125] op_sel_hi:[0,1,1]
	v_pk_fma_f32 v[126:127], v[54:55], v[34:35], v[126:127] op_sel_hi:[0,1,1]
	global_store_dwordx4 v175, v[112:115], s[100:101]
	global_store_dwordx4 v175, v[116:119], s[100:101] offset:1024
	global_store_dwordx4 v175, v[120:123], s[100:101] offset:2048
	global_store_dwordx4 v175, v[124:127], s[100:101] offset:3072
	v_add_u32_e32 v175, 0x800000, v175
	global_load_dword v52, v172, s[98:99]
	global_load_dwordx2 v[20:21], v170, s[98:99]
	global_load_dwordx2 v[22:23], v170, s[98:99] offset:512
	global_load_dwordx2 v[24:25], v170, s[98:99] offset:1024
	global_load_dwordx2 v[26:27], v170, s[98:99] offset:1536
	global_load_dwordx2 v[36:37], v171, s[98:99]
	global_load_dwordx2 v[38:39], v171, s[98:99] offset:512
	global_load_dwordx2 v[40:41], v171, s[98:99] offset:1024
	global_load_dwordx2 v[42:43], v171, s[98:99] offset:1536
	v_add_u32_e32 v170, 0x400000, v170
	v_add_u32_e32 v171, 0x400000, v171
	v_add_u32_e32 v172, 0x2000, v172
	global_load_dword v54, v172, s[98:99]
	global_load_dwordx2 v[28:29], v170, s[98:99]
	global_load_dwordx2 v[30:31], v170, s[98:99] offset:512
	global_load_dwordx2 v[32:33], v170, s[98:99] offset:1024
	global_load_dwordx2 v[34:35], v170, s[98:99] offset:1536
	global_load_dwordx2 v[44:45], v171, s[98:99]
	global_load_dwordx2 v[46:47], v171, s[98:99] offset:512
	global_load_dwordx2 v[48:49], v171, s[98:99] offset:1024
	global_load_dwordx2 v[50:51], v171, s[98:99] offset:1536
	v_add_u32_e32 v170, 0x400000, v170
	v_add_u32_e32 v171, 0x400000, v171
	v_add_u32_e32 v172, 0x2000, v172
	s_waitcnt vmcnt(39)
	v_lshlrev_b32_e32 v96, 16, v56
	v_and_b32_e32 v97, 0xffff0000, v56
	v_lshlrev_b32_e32 v98, 16, v57
	v_and_b32_e32 v99, 0xffff0000, v57
	v_lshlrev_b32_e32 v100, 16, v58
	v_and_b32_e32 v101, 0xffff0000, v58
	v_lshlrev_b32_e32 v102, 16, v59
	v_and_b32_e32 v103, 0xffff0000, v59
	v_lshlrev_b32_e32 v104, 16, v60
	v_and_b32_e32 v105, 0xffff0000, v60
	v_lshlrev_b32_e32 v106, 16, v61
	v_and_b32_e32 v107, 0xffff0000, v61
	v_lshlrev_b32_e32 v108, 16, v62
	v_and_b32_e32 v109, 0xffff0000, v62
	v_lshlrev_b32_e32 v110, 16, v63
	v_and_b32_e32 v111, 0xffff0000, v63
	v_pk_mul_f32 v[128:129], v[96:97], v[96:97]
	v_pk_fma_f32 v[128:129], v[98:99], v[98:99], v[128:129]
	v_pk_fma_f32 v[128:129], v[100:101], v[100:101], v[128:129]
	v_pk_fma_f32 v[128:129], v[102:103], v[102:103], v[128:129]
	v_pk_fma_f32 v[128:129], v[104:105], v[104:105], v[128:129]
	v_pk_fma_f32 v[128:129], v[106:107], v[106:107], v[128:129]
	v_pk_fma_f32 v[128:129], v[108:109], v[108:109], v[128:129]
	v_pk_fma_f32 v[128:129], v[110:111], v[110:111], v[128:129]
	s_nop 0
	v_add_f32_e32 v128, v128, v129
	s_waitcnt vmcnt(30)
	v_lshlrev_b32_e32 v112, 16, v64
	v_and_b32_e32 v113, 0xffff0000, v64
	v_lshlrev_b32_e32 v114, 16, v65
	v_and_b32_e32 v115, 0xffff0000, v65
	v_lshlrev_b32_e32 v116, 16, v66
	v_and_b32_e32 v117, 0xffff0000, v66
	v_lshlrev_b32_e32 v118, 16, v67
	v_and_b32_e32 v119, 0xffff0000, v67
	v_lshlrev_b32_e32 v120, 16, v68
	v_and_b32_e32 v121, 0xffff0000, v68
	v_lshlrev_b32_e32 v122, 16, v69
	v_and_b32_e32 v123, 0xffff0000, v69
	v_lshlrev_b32_e32 v124, 16, v70
	v_and_b32_e32 v125, 0xffff0000, v70
	v_lshlrev_b32_e32 v126, 16, v71
	v_and_b32_e32 v127, 0xffff0000, v71
	v_pk_mul_f32 v[130:131], v[112:113], v[112:113]
	v_pk_fma_f32 v[130:131], v[114:115], v[114:115], v[130:131]
	v_pk_fma_f32 v[130:131], v[116:117], v[116:117], v[130:131]
	v_pk_fma_f32 v[130:131], v[118:119], v[118:119], v[130:131]
	v_pk_fma_f32 v[130:131], v[120:121], v[120:121], v[130:131]
	v_pk_fma_f32 v[130:131], v[122:123], v[122:123], v[130:131]
	v_pk_fma_f32 v[130:131], v[124:125], v[124:125], v[130:131]
	v_pk_fma_f32 v[130:131], v[126:127], v[126:127], v[130:131]
	s_nop 0
	v_add_f32_e32 v130, v130, v131
	s_nop 1
	v_add_f32_dpp v128, v128, v128 quad_perm:[1,0,3,2] row_mask:0xf bank_mask:0xf
	v_add_f32_dpp v130, v130, v130 quad_perm:[1,0,3,2] row_mask:0xf bank_mask:0xf
	s_nop 0
	v_add_f32_dpp v128, v128, v128 quad_perm:[2,3,0,1] row_mask:0xf bank_mask:0xf
	v_add_f32_dpp v130, v130, v130 quad_perm:[2,3,0,1] row_mask:0xf bank_mask:0xf
	s_nop 0
	v_add_f32_dpp v128, v128, v128 row_half_mirror row_mask:0xf bank_mask:0xf
	v_add_f32_dpp v130, v130, v130 row_half_mirror row_mask:0xf bank_mask:0xf
	s_nop 0
	v_add_f32_dpp v128, v128, v128 row_mirror row_mask:0xf bank_mask:0xf
	v_add_f32_dpp v130, v130, v130 row_mirror row_mask:0xf bank_mask:0xf
	s_nop 0
	ds_bpermute_b32 v136, v187, v128
	ds_bpermute_b32 v137, v187, v130
	s_waitcnt lgkmcnt(0)
	v_add_f32_e32 v128, v128, v136
	v_add_f32_e32 v130, v130, v137
	ds_bpermute_b32 v136, v188, v128
	ds_bpermute_b32 v137, v188, v130
	s_waitcnt lgkmcnt(0)
;     __device__ __forceinline__ float* out() const { return (float*)karg_in(33); }
; __device__ __forceinline__ const float* xrow_ptr(const Ctx& C, int row) { return row < MPROMPT ? C.in(0) + (size_t)row * DM : C.in(1) + (size_t)(row - MPROMPT) * DM; }
; __device__ __forceinline__ v4f ld4_bf16(const bf16* p) { const v2u w = *(const v2u*)p; return (v4f){bf_lo(w.x), bf_hi(w.x), bf_lo(w.y), bf_hi(w.y)}; }
; __device__ __forceinline__ float ssq4(v4f v) { return (v.x * v.x + v.y * v.y) + (v.z * v.z + v.w * v.w); }
; template <int R, bool BASE_F32, bool OUT_F32>
; __device__ __forceinline__ void rows_res(const Ctx& C, int m0, int stride, int mx, const float* gpost, float scale, int lane) {
;     ...
;     for (int r = 0; r < R; ++r) { mr[r] = (r == 4) ? mx : m0 + r * stride; ok[r] = (r == 4) ? (mx < M) : (mr[r] < MPROMPT); const int mm = ok[r] ? mr[r] : 0;
; #pragma unroll
;         for (int j = 0; j < 4; ++j) d[r][j] = ld4_bf16(D + (size_t)mm * DM + 4 * lane + 256 * j);
;         if (BASE_F32) { const float* x = xrow_ptr(C, mm);
; #pragma unroll
;             for (int j = 0; j < 4; ++j) b[r][j] = ld4_f32(x + 4 * lane + 256 * j);
;         } else { const float inv = C.RS()[mm];
; #pragma unroll
;             for (int j = 0; j < 4; ++j) b[r][j] = ld4_bf16(XN + (size_t)mm * DM + 4 * lane + 256 * j) * inv;
;         } }
; #pragma unroll
;     for (int r = 0; r < R; ++r) { float s = 0.f;
; #pragma unroll
;         for (int j = 0; j < 4; ++j) s += ssq4(d[r][j]);
;         r1[r] = s; }
; #pragma unroll
;     for (int r = 0; r < R; ++r) r1[r] = rsqrtf(wave_sum(r1[r]) * (1.f / DM) + EPS) * scale;
; #pragma unroll
;     for (int j = 0; j < 4; ++j) { const v4f gp = ld4_f32(gpost + 4 * lane + 256 * j);
; #pragma unroll
;         for (int r = 0; r < R; ++r) d[r][j] = b[r][j] + d[r][j] * r1[r] * gp; }
;     if (OUT_F32) { float* Y = C.out();
; #pragma unroll
;         for (int r = 0; r < R; ++r)
; #pragma unroll
;             for (int j = 0; j < 4; ++j) if (ok[r]) *(v4f*)(Y + (size_t)mr[r] * DM + 4 * lane + 256 * j) = d[r][j];
	v_add_f32_e32 v128, v128, v136
	v_add_f32_e32 v130, v130, v137
	v_fmamk_f32 v128, v128, 0x3a800000, v138
	v_fmamk_f32 v130, v130, 0x3a800000, v138
	s_nop 0
	v_rsq_f32_e32 v128, v128
	v_rsq_f32_e32 v130, v130
	s_nop 1
	v_mul_f32_e32 v128, 0.5, v128
	v_mul_f32_e32 v130, 0.5, v130
	s_waitcnt vmcnt(26)
	v_pk_mul_f32 v[96:97], v[128:129], v[96:97] op_sel_hi:[0,1]
	v_pk_mul_f32 v[98:99], v[128:129], v[98:99] op_sel_hi:[0,1]
	v_pk_mul_f32 v[100:101], v[128:129], v[100:101] op_sel_hi:[0,1]
	v_pk_mul_f32 v[102:103], v[128:129], v[102:103] op_sel_hi:[0,1]
	v_pk_mul_f32 v[104:105], v[128:129], v[104:105] op_sel_hi:[0,1]
	v_pk_mul_f32 v[106:107], v[128:129], v[106:107] op_sel_hi:[0,1]
	v_pk_mul_f32 v[108:109], v[128:129], v[108:109] op_sel_hi:[0,1]
	v_pk_mul_f32 v[110:111], v[128:129], v[110:111] op_sel_hi:[0,1]
	v_pk_mul_f32 v[96:97], v[96:97], v[192:193]
	v_pk_mul_f32 v[98:99], v[98:99], v[194:195]
	v_pk_mul_f32 v[100:101], v[100:101], v[196:197]
	v_pk_mul_f32 v[102:103], v[102:103], v[198:199]
	v_pk_mul_f32 v[104:105], v[104:105], v[200:201]
	v_pk_mul_f32 v[106:107], v[106:107], v[202:203]
	v_pk_mul_f32 v[108:109], v[108:109], v[204:205]
	v_pk_mul_f32 v[110:111], v[110:111], v[206:207]
	v_lshlrev_b32_e32 v56, 16, v72
	v_and_b32_e32 v57, 0xffff0000, v72
	v_lshlrev_b32_e32 v58, 16, v73
	v_and_b32_e32 v59, 0xffff0000, v73
	v_lshlrev_b32_e32 v60, 16, v74
	v_and_b32_e32 v61, 0xffff0000, v74
	v_lshlrev_b32_e32 v62, 16, v75
	v_and_b32_e32 v63, 0xffff0000, v75
	v_pk_fma_f32 v[96:97], v[88:89], v[56:57], v[96:97] op_sel_hi:[0,1,1]
	v_pk_fma_f32 v[98:99], v[88:89], v[58:59], v[98:99] op_sel_hi:[0,1,1]
	v_pk_fma_f32 v[100:101], v[88:89], v[60:61], v[100:101] op_sel_hi:[0,1,1]
	v_pk_fma_f32 v[102:103], v[88:89], v[62:63], v[102:103] op_sel_hi:[0,1,1]
	v_lshlrev_b32_e32 v56, 16, v76
	v_and_b32_e32 v57, 0xffff0000, v76
	v_lshlrev_b32_e32 v58, 16, v77
	v_and_b32_e32 v59, 0xffff0000, v77
	v_lshlrev_b32_e32 v60, 16, v78
	v_and_b32_e32 v61, 0xffff0000, v78
	v_lshlrev_b32_e32 v62, 16, v79
	v_and_b32_e32 v63, 0xffff0000, v79
	v_pk_fma_f32 v[104:105], v[88:89], v[56:57], v[104:105] op_sel_hi:[0,1,1]
	v_pk_fma_f32 v[106:107], v[88:89], v[58:59], v[106:107] op_sel_hi:[0,1,1]
	v_pk_fma_f32 v[108:109], v[88:89], v[60:61], v[108:109] op_sel_hi:[0,1,1]
	v_pk_fma_f32 v[110:111], v[88:89], v[62:63], v[110:111] op_sel_hi:[0,1,1]
	global_store_dwordx4 v175, v[96:99], s[100:101]
	global_store_dwordx4 v175, v[100:103], s[100:101] offset:1024
	global_store_dwordx4 v175, v[104:107], s[100:101] offset:2048
	global_store_dwordx4 v175, v[108:111], s[100:101] offset:3072
	v_add_u32_e32 v175, 0x800000, v175
	v_pk_mul_f32 v[112:113], v[130:131], v[112:113] op_sel_hi:[0,1]
	v_pk_mul_f32 v[114:115], v[130:131], v[114:115] op_sel_hi:[0,1]
	v_pk_mul_f32 v[116:117], v[130:131], v[116:117] op_sel_hi:[0,1]
	v_pk_mul_f32 v[118:119], v[130:131], v[118:119] op_sel_hi:[0,1]
	v_pk_mul_f32 v[120:121], v[130:131], v[120:121] op_sel_hi:[0,1]
	v_pk_mul_f32 v[122:123], v[130:131], v[122:123] op_sel_hi:[0,1]
	v_pk_mul_f32 v[124:125], v[130:131], v[124:125] op_sel_hi:[0,1]
	v_pk_mul_f32 v[126:127], v[130:131], v[126:127] op_sel_hi:[0,1]
	v_pk_mul_f32 v[112:113], v[112:113], v[192:193]
	v_pk_mul_f32 v[114:115], v[114:115], v[194:195]
	v_pk_mul_f32 v[116:117], v[116:117], v[196:197]
	v_pk_mul_f32 v[118:119], v[118:119], v[198:199]
	v_pk_mul_f32 v[120:121], v[120:121], v[200:201]
	v_pk_mul_f32 v[122:123], v[122:123], v[202:203]
	v_pk_mul_f32 v[124:125], v[124:125], v[204:205]
	v_pk_mul_f32 v[126:127], v[126:127], v[206:207]
	v_lshlrev_b32_e32 v64, 16, v80
	v_and_b32_e32 v65, 0xffff0000, v80
	v_lshlrev_b32_e32 v66, 16, v81
	v_and_b32_e32 v67, 0xffff0000, v81
	v_lshlrev_b32_e32 v68, 16, v82
	v_and_b32_e32 v69, 0xffff0000, v82
	v_lshlrev_b32_e32 v70, 16, v83
	v_and_b32_e32 v71, 0xffff0000, v83
	v_pk_fma_f32 v[112:113], v[90:91], v[64:65], v[112:113] op_sel_hi:[0,1,1]
	v_pk_fma_f32 v[114:115], v[90:91], v[66:67], v[114:115] op_sel_hi:[0,1,1]
	v_pk_fma_f32 v[116:117], v[90:91], v[68:69], v[116:117] op_sel_hi:[0,1,1]
	v_pk_fma_f32 v[118:119], v[90:91], v[70:71], v[118:119] op_sel_hi:[0,1,1]
	v_lshlrev_b32_e32 v64, 16, v84
	v_and_b32_e32 v65, 0xffff0000, v84
	v_lshlrev_b32_e32 v66, 16, v85
	v_and_b32_e32 v67, 0xffff0000, v85
	v_lshlrev_b32_e32 v68, 16, v86
	v_and_b32_e32 v69, 0xffff0000, v86
	v_lshlrev_b32_e32 v70, 16, v87
	v_and_b32_e32 v71, 0xffff0000, v87
	v_pk_fma_f32 v[120:121], v[90:91], v[64:65], v[120:121] op_sel_hi:[0,1,1]
	v_pk_fma_f32 v[122:123], v[90:91], v[66:67], v[122:123] op_sel_hi:[0,1,1]
	v_pk_fma_f32 v[124:125], v[90:91], v[68:69], v[124:125] op_sel_hi:[0,1,1]
	v_pk_fma_f32 v[126:127], v[90:91], v[70:71], v[126:127] op_sel_hi:[0,1,1]
	global_store_dwordx4 v175, v[112:115], s[100:101]
	global_store_dwordx4 v175, v[116:119], s[100:101] offset:1024
	global_store_dwordx4 v175, v[120:123], s[100:101] offset:2048
	global_store_dwordx4 v175, v[124:127], s[100:101] offset:3072
	v_add_u32_e32 v175, 0x800000, v175
	global_load_dword v88, v172, s[98:99]
	global_load_dwordx2 v[56:57], v170, s[98:99]
	global_load_dwordx2 v[58:59], v170, s[98:99] offset:512
	global_load_dwordx2 v[60:61], v170, s[98:99] offset:1024
	global_load_dwordx2 v[62:63], v170, s[98:99] offset:1536
	global_load_dwordx2 v[72:73], v171, s[98:99]
	global_load_dwordx2 v[74:75], v171, s[98:99] offset:512
	global_load_dwordx2 v[76:77], v171, s[98:99] offset:1024
	global_load_dwordx2 v[78:79], v171, s[98:99] offset:1536
	v_add_u32_e32 v170, 0x400000, v170
	v_add_u32_e32 v171, 0x400000, v171
	v_add_u32_e32 v172, 0x2000, v172
	global_load_dword v90, v172, s[98:99]
	global_load_dwordx2 v[64:65], v170, s[98:99]
	global_load_dwordx2 v[66:67], v170, s[98:99] offset:512
	global_load_dwordx2 v[68:69], v170, s[98:99] offset:1024
	global_load_dwordx2 v[70:71], v170, s[98:99] offset:1536
	global_load_dwordx2 v[80:81], v171, s[98:99]
	global_load_dwordx2 v[82:83], v171, s[98:99] offset:512
	global_load_dwordx2 v[84:85], v171, s[98:99] offset:1024
	global_load_dwordx2 v[86:87], v171, s[98:99] offset:1536
	v_add_u32_e32 v170, 0x400000, v170
	v_add_u32_e32 v171, 0x400000, v171
	v_add_u32_e32 v172, 0x2000, v172
	s_waitcnt vmcnt(39)
;     __device__ __forceinline__ float* out() const { return (float*)karg_in(33); }
; __device__ __forceinline__ float ssq4(v4f v) { return (v.x * v.x + v.y * v.y) + (v.z * v.z + v.w * v.w); }
; template <int R, bool BASE_F32, bool OUT_F32>
; __device__ __forceinline__ void rows_res(const Ctx& C, int m0, int stride, int mx, const float* gpost, float scale, int lane) {
;     ...
;     for (int r = 0; r < R; ++r) { float s = 0.f;
; #pragma unroll
;         for (int j = 0; j < 4; ++j) s += ssq4(d[r][j]);
;         r1[r] = s; }
; #pragma unroll
;     for (int r = 0; r < R; ++r) r1[r] = rsqrtf(wave_sum(r1[r]) * (1.f / DM) + EPS) * scale;
; #pragma unroll
;     for (int j = 0; j < 4; ++j) { const v4f gp = ld4_f32(gpost + 4 * lane + 256 * j);
; #pragma unroll
;         for (int r = 0; r < R; ++r) d[r][j] = b[r][j] + d[r][j] * r1[r] * gp; }
;     if (OUT_F32) { float* Y = C.out();
; #pragma unroll
;         for (int r = 0; r < R; ++r)
; #pragma unroll
;             for (int j = 0; j < 4; ++j) if (ok[r]) *(v4f*)(Y + (size_t)mr[r] * DM + 4 * lane + 256 * j) = d[r][j];
	v_lshlrev_b32_e32 v96, 16, v20
	v_and_b32_e32 v97, 0xffff0000, v20
	v_lshlrev_b32_e32 v98, 16, v21
	v_and_b32_e32 v99, 0xffff0000, v21
	v_lshlrev_b32_e32 v100, 16, v22
	v_and_b32_e32 v101, 0xffff0000, v22
	v_lshlrev_b32_e32 v102, 16, v23
	v_and_b32_e32 v103, 0xffff0000, v23
	v_lshlrev_b32_e32 v104, 16, v24
	v_and_b32_e32 v105, 0xffff0000, v24
	v_lshlrev_b32_e32 v106, 16, v25
	v_and_b32_e32 v107, 0xffff0000, v25
	v_lshlrev_b32_e32 v108, 16, v26
	v_and_b32_e32 v109, 0xffff0000, v26
	v_lshlrev_b32_e32 v110, 16, v27
	v_and_b32_e32 v111, 0xffff0000, v27
	v_pk_mul_f32 v[128:129], v[96:97], v[96:97]
	v_pk_fma_f32 v[128:129], v[98:99], v[98:99], v[128:129]
	v_pk_fma_f32 v[128:129], v[100:101], v[100:101], v[128:129]
	v_pk_fma_f32 v[128:129], v[102:103], v[102:103], v[128:129]
	v_pk_fma_f32 v[128:129], v[104:105], v[104:105], v[128:129]
	v_pk_fma_f32 v[128:129], v[106:107], v[106:107], v[128:129]
	v_pk_fma_f32 v[128:129], v[108:109], v[108:109], v[128:129]
	v_pk_fma_f32 v[128:129], v[110:111], v[110:111], v[128:129]
	s_nop 0
	v_add_f32_e32 v128, v128, v129
	s_waitcnt vmcnt(30)
	v_lshlrev_b32_e32 v112, 16, v28
	v_and_b32_e32 v113, 0xffff0000, v28
	v_lshlrev_b32_e32 v114, 16, v29
	v_and_b32_e32 v115, 0xffff0000, v29
	v_lshlrev_b32_e32 v116, 16, v30
	v_and_b32_e32 v117, 0xffff0000, v30
	v_lshlrev_b32_e32 v118, 16, v31
	v_and_b32_e32 v119, 0xffff0000, v31
	v_lshlrev_b32_e32 v120, 16, v32
	v_and_b32_e32 v121, 0xffff0000, v32
	v_lshlrev_b32_e32 v122, 16, v33
	v_and_b32_e32 v123, 0xffff0000, v33
	v_lshlrev_b32_e32 v124, 16, v34
	v_and_b32_e32 v125, 0xffff0000, v34
	v_lshlrev_b32_e32 v126, 16, v35
	v_and_b32_e32 v127, 0xffff0000, v35
	v_pk_mul_f32 v[130:131], v[112:113], v[112:113]
	v_pk_fma_f32 v[130:131], v[114:115], v[114:115], v[130:131]
	v_pk_fma_f32 v[130:131], v[116:117], v[116:117], v[130:131]
	v_pk_fma_f32 v[130:131], v[118:119], v[118:119], v[130:131]
	v_pk_fma_f32 v[130:131], v[120:121], v[120:121], v[130:131]
	v_pk_fma_f32 v[130:131], v[122:123], v[122:123], v[130:131]
	v_pk_fma_f32 v[130:131], v[124:125], v[124:125], v[130:131]
	v_pk_fma_f32 v[130:131], v[126:127], v[126:127], v[130:131]
	s_nop 0
	v_add_f32_e32 v130, v130, v131
	s_nop 1
	v_add_f32_dpp v128, v128, v128 quad_perm:[1,0,3,2] row_mask:0xf bank_mask:0xf
	v_add_f32_dpp v130, v130, v130 quad_perm:[1,0,3,2] row_mask:0xf bank_mask:0xf
	s_nop 0
	v_add_f32_dpp v128, v128, v128 quad_perm:[2,3,0,1] row_mask:0xf bank_mask:0xf
	v_add_f32_dpp v130, v130, v130 quad_perm:[2,3,0,1] row_mask:0xf bank_mask:0xf
	s_nop 0
	v_add_f32_dpp v128, v128, v128 row_half_mirror row_mask:0xf bank_mask:0xf
	v_add_f32_dpp v130, v130, v130 row_half_mirror row_mask:0xf bank_mask:0xf
	s_nop 0
	v_add_f32_dpp v128, v128, v128 row_mirror row_mask:0xf bank_mask:0xf
	v_add_f32_dpp v130, v130, v130 row_mirror row_mask:0xf bank_mask:0xf
	s_nop 0
	ds_bpermute_b32 v136, v187, v128
	ds_bpermute_b32 v137, v187, v130
	s_waitcnt lgkmcnt(0)
	v_add_f32_e32 v128, v128, v136
	v_add_f32_e32 v130, v130, v137
	ds_bpermute_b32 v136, v188, v128
	ds_bpermute_b32 v137, v188, v130
	s_waitcnt lgkmcnt(0)
	v_add_f32_e32 v128, v128, v136
	v_add_f32_e32 v130, v130, v137
	v_fmamk_f32 v128, v128, 0x3a800000, v138
	v_fmamk_f32 v130, v130, 0x3a800000, v138
	s_nop 0
	v_rsq_f32_e32 v128, v128
	v_rsq_f32_e32 v130, v130
	s_nop 1
	v_mul_f32_e32 v128, 0.5, v128
	v_mul_f32_e32 v130, 0.5, v130
	s_waitcnt vmcnt(26)
	v_pk_mul_f32 v[96:97], v[128:129], v[96:97] op_sel_hi:[0,1]
	v_pk_mul_f32 v[98:99], v[128:129], v[98:99] op_sel_hi:[0,1]
	v_pk_mul_f32 v[100:101], v[128:129], v[100:101] op_sel_hi:[0,1]
	v_pk_mul_f32 v[102:103], v[128:129], v[102:103] op_sel_hi:[0,1]
	v_pk_mul_f32 v[104:105], v[128:129], v[104:105] op_sel_hi:[0,1]
	v_pk_mul_f32 v[106:107], v[128:129], v[106:107] op_sel_hi:[0,1]
	v_pk_mul_f32 v[108:109], v[128:129], v[108:109] op_sel_hi:[0,1]
	v_pk_mul_f32 v[110:111], v[128:129], v[110:111] op_sel_hi:[0,1]
	v_pk_mul_f32 v[96:97], v[96:97], v[192:193]
	v_pk_mul_f32 v[98:99], v[98:99], v[194:195]
	v_pk_mul_f32 v[100:101], v[100:101], v[196:197]
	v_pk_mul_f32 v[102:103], v[102:103], v[198:199]
	v_pk_mul_f32 v[104:105], v[104:105], v[200:201]
	v_pk_mul_f32 v[106:107], v[106:107], v[202:203]
	v_pk_mul_f32 v[108:109], v[108:109], v[204:205]
	v_pk_mul_f32 v[110:111], v[110:111], v[206:207]
	v_lshlrev_b32_e32 v20, 16, v36
	v_and_b32_e32 v21, 0xffff0000, v36
	v_lshlrev_b32_e32 v22, 16, v37
	v_and_b32_e32 v23, 0xffff0000, v37
	v_lshlrev_b32_e32 v24, 16, v38
	v_and_b32_e32 v25, 0xffff0000, v38
	v_lshlrev_b32_e32 v26, 16, v39
	v_and_b32_e32 v27, 0xffff0000, v39
	v_pk_fma_f32 v[96:97], v[52:53], v[20:21], v[96:97] op_sel_hi:[0,1,1]
	v_pk_fma_f32 v[98:99], v[52:53], v[22:23], v[98:99] op_sel_hi:[0,1,1]
	v_pk_fma_f32 v[100:101], v[52:53], v[24:25], v[100:101] op_sel_hi:[0,1,1]
	v_pk_fma_f32 v[102:103], v[52:53], v[26:27], v[102:103] op_sel_hi:[0,1,1]
	v_lshlrev_b32_e32 v20, 16, v40
	v_and_b32_e32 v21, 0xffff0000, v40
	v_lshlrev_b32_e32 v22, 16, v41
	v_and_b32_e32 v23, 0xffff0000, v41
	v_lshlrev_b32_e32 v24, 16, v42
	v_and_b32_e32 v25, 0xffff0000, v42
	v_lshlrev_b32_e32 v26, 16, v43
	v_and_b32_e32 v27, 0xffff0000, v43
	v_pk_fma_f32 v[104:105], v[52:53], v[20:21], v[104:105] op_sel_hi:[0,1,1]
	v_pk_fma_f32 v[106:107], v[52:53], v[22:23], v[106:107] op_sel_hi:[0,1,1]
	v_pk_fma_f32 v[108:109], v[52:53], v[24:25], v[108:109] op_sel_hi:[0,1,1]
	v_pk_fma_f32 v[110:111], v[52:53], v[26:27], v[110:111] op_sel_hi:[0,1,1]
	global_store_dwordx4 v175, v[96:99], s[100:101]
	global_store_dwordx4 v175, v[100:103], s[100:101] offset:1024
	global_store_dwordx4 v175, v[104:107], s[100:101] offset:2048
	global_store_dwordx4 v175, v[108:111], s[100:101] offset:3072
;     __device__ __forceinline__ float* out() const { return (float*)karg_in(33); }
; __device__ __forceinline__ const float* xrow_ptr(const Ctx& C, int row) { return row < MPROMPT ? C.in(0) + (size_t)row * DM : C.in(1) + (size_t)(row - MPROMPT) * DM; }
; __device__ __forceinline__ v4f ld4_bf16(const bf16* p) { const v2u w = *(const v2u*)p; return (v4f){bf_lo(w.x), bf_hi(w.x), bf_lo(w.y), bf_hi(w.y)}; }
; __device__ __forceinline__ float ssq4(v4f v) { return (v.x * v.x + v.y * v.y) + (v.z * v.z + v.w * v.w); }
; template <int R, bool BASE_F32, bool OUT_F32>
; __device__ __forceinline__ void rows_res(const Ctx& C, int m0, int stride, int mx, const float* gpost, float scale, int lane) {
;     ...
;     for (int r = 0; r < R; ++r) { mr[r] = (r == 4) ? mx : m0 + r * stride; ok[r] = (r == 4) ? (mx < M) : (mr[r] < MPROMPT); const int mm = ok[r] ? mr[r] : 0;
; #pragma unroll
;         for (int j = 0; j < 4; ++j) d[r][j] = ld4_bf16(D + (size_t)mm * DM + 4 * lane + 256 * j);
;         if (BASE_F32) { const float* x = xrow_ptr(C, mm);
; #pragma unroll
;             for (int j = 0; j < 4; ++j) b[r][j] = ld4_f32(x + 4 * lane + 256 * j);
;         } else { const float inv = C.RS()[mm];
; #pragma unroll
;             for (int j = 0; j < 4; ++j) b[r][j] = ld4_bf16(XN + (size_t)mm * DM + 4 * lane + 256 * j) * inv;
;         } }
; #pragma unroll
;     for (int r = 0; r < R; ++r) { float s = 0.f;
; #pragma unroll
;         for (int j = 0; j < 4; ++j) s += ssq4(d[r][j]);
;         r1[r] = s; }
; #pragma unroll
;     for (int r = 0; r < R; ++r) r1[r] = rsqrtf(wave_sum(r1[r]) * (1.f / DM) + EPS) * scale;
; #pragma unroll
;     for (int j = 0; j < 4; ++j) { const v4f gp = ld4_f32(gpost + 4 * lane + 256 * j);
; #pragma unroll
;         for (int r = 0; r < R; ++r) d[r][j] = b[r][j] + d[r][j] * r1[r] * gp; }
;     if (OUT_F32) { float* Y = C.out();
; #pragma unroll
;         for (int r = 0; r < R; ++r)
; #pragma unroll
;             for (int j = 0; j < 4; ++j) if (ok[r]) *(v4f*)(Y + (size_t)mr[r] * DM + 4 * lane + 256 * j) = d[r][j];
	v_add_u32_e32 v175, 0x800000, v175
	v_pk_mul_f32 v[112:113], v[130:131], v[112:113] op_sel_hi:[0,1]
	v_pk_mul_f32 v[114:115], v[130:131], v[114:115] op_sel_hi:[0,1]
	v_pk_mul_f32 v[116:117], v[130:131], v[116:117] op_sel_hi:[0,1]
	v_pk_mul_f32 v[118:119], v[130:131], v[118:119] op_sel_hi:[0,1]
	v_pk_mul_f32 v[120:121], v[130:131], v[120:121] op_sel_hi:[0,1]
	v_pk_mul_f32 v[122:123], v[130:131], v[122:123] op_sel_hi:[0,1]
	v_pk_mul_f32 v[124:125], v[130:131], v[124:125] op_sel_hi:[0,1]
	v_pk_mul_f32 v[126:127], v[130:131], v[126:127] op_sel_hi:[0,1]
	v_pk_mul_f32 v[112:113], v[112:113], v[192:193]
	v_pk_mul_f32 v[114:115], v[114:115], v[194:195]
	v_pk_mul_f32 v[116:117], v[116:117], v[196:197]
	v_pk_mul_f32 v[118:119], v[118:119], v[198:199]
	v_pk_mul_f32 v[120:121], v[120:121], v[200:201]
	v_pk_mul_f32 v[122:123], v[122:123], v[202:203]
	v_pk_mul_f32 v[124:125], v[124:125], v[204:205]
	v_pk_mul_f32 v[126:127], v[126:127], v[206:207]
	v_lshlrev_b32_e32 v28, 16, v44
	v_and_b32_e32 v29, 0xffff0000, v44
	v_lshlrev_b32_e32 v30, 16, v45
	v_and_b32_e32 v31, 0xffff0000, v45
	v_lshlrev_b32_e32 v32, 16, v46
	v_and_b32_e32 v33, 0xffff0000, v46
	v_lshlrev_b32_e32 v34, 16, v47
	v_and_b32_e32 v35, 0xffff0000, v47
	v_pk_fma_f32 v[112:113], v[54:55], v[28:29], v[112:113] op_sel_hi:[0,1,1]
	v_pk_fma_f32 v[114:115], v[54:55], v[30:31], v[114:115] op_sel_hi:[0,1,1]
	v_pk_fma_f32 v[116:117], v[54:55], v[32:33], v[116:117] op_sel_hi:[0,1,1]
	v_pk_fma_f32 v[118:119], v[54:55], v[34:35], v[118:119] op_sel_hi:[0,1,1]
	v_lshlrev_b32_e32 v28, 16, v48
	v_and_b32_e32 v29, 0xffff0000, v48
	v_lshlrev_b32_e32 v30, 16, v49
	v_and_b32_e32 v31, 0xffff0000, v49
	v_lshlrev_b32_e32 v32, 16, v50
	v_and_b32_e32 v33, 0xffff0000, v50
	v_lshlrev_b32_e32 v34, 16, v51
	v_and_b32_e32 v35, 0xffff0000, v51
	v_pk_fma_f32 v[120:121], v[54:55], v[28:29], v[120:121] op_sel_hi:[0,1,1]
	v_pk_fma_f32 v[122:123], v[54:55], v[30:31], v[122:123] op_sel_hi:[0,1,1]
	v_pk_fma_f32 v[124:125], v[54:55], v[32:33], v[124:125] op_sel_hi:[0,1,1]
	v_pk_fma_f32 v[126:127], v[54:55], v[34:35], v[126:127] op_sel_hi:[0,1,1]
	global_store_dwordx4 v175, v[112:115], s[100:101]
	global_store_dwordx4 v175, v[116:119], s[100:101] offset:1024
	global_store_dwordx4 v175, v[120:123], s[100:101] offset:2048
	global_store_dwordx4 v175, v[124:127], s[100:101] offset:3072
	v_add_u32_e32 v175, 0x800000, v175
	global_load_dword v52, v172, s[98:99]
	global_load_dwordx2 v[20:21], v170, s[98:99]
	global_load_dwordx2 v[22:23], v170, s[98:99] offset:512
	global_load_dwordx2 v[24:25], v170, s[98:99] offset:1024
	global_load_dwordx2 v[26:27], v170, s[98:99] offset:1536
	global_load_dwordx2 v[36:37], v171, s[98:99]
	global_load_dwordx2 v[38:39], v171, s[98:99] offset:512
	global_load_dwordx2 v[40:41], v171, s[98:99] offset:1024
	global_load_dwordx2 v[42:43], v171, s[98:99] offset:1536
	v_add_u32_e32 v170, 0x400000, v170
	v_add_u32_e32 v171, 0x400000, v171
	v_add_u32_e32 v172, 0x2000, v172
	global_load_dword v54, v172, s[98:99]
	global_load_dwordx2 v[28:29], v170, s[98:99]
	global_load_dwordx2 v[30:31], v170, s[98:99] offset:512
	global_load_dwordx2 v[32:33], v170, s[98:99] offset:1024
	global_load_dwordx2 v[34:35], v170, s[98:99] offset:1536
	global_load_dwordx2 v[44:45], v171, s[98:99]
	global_load_dwordx2 v[46:47], v171, s[98:99] offset:512
	global_load_dwordx2 v[48:49], v171, s[98:99] offset:1024
	global_load_dwordx2 v[50:51], v171, s[98:99] offset:1536
	v_add_u32_e32 v170, 0x400000, v170
	v_add_u32_e32 v171, 0x400000, v171
	v_add_u32_e32 v172, 0x2000, v172
	s_waitcnt vmcnt(39)
	v_lshlrev_b32_e32 v96, 16, v56
	v_and_b32_e32 v97, 0xffff0000, v56
	v_lshlrev_b32_e32 v98, 16, v57
	v_and_b32_e32 v99, 0xffff0000, v57
	v_lshlrev_b32_e32 v100, 16, v58
	v_and_b32_e32 v101, 0xffff0000, v58
	v_lshlrev_b32_e32 v102, 16, v59
	v_and_b32_e32 v103, 0xffff0000, v59
	v_lshlrev_b32_e32 v104, 16, v60
	v_and_b32_e32 v105, 0xffff0000, v60
	v_lshlrev_b32_e32 v106, 16, v61
	v_and_b32_e32 v107, 0xffff0000, v61
	v_lshlrev_b32_e32 v108, 16, v62
	v_and_b32_e32 v109, 0xffff0000, v62
	v_lshlrev_b32_e32 v110, 16, v63
	v_and_b32_e32 v111, 0xffff0000, v63
	v_pk_mul_f32 v[128:129], v[96:97], v[96:97]
	v_pk_fma_f32 v[128:129], v[98:99], v[98:99], v[128:129]
	v_pk_fma_f32 v[128:129], v[100:101], v[100:101], v[128:129]
	v_pk_fma_f32 v[128:129], v[102:103], v[102:103], v[128:129]
	v_pk_fma_f32 v[128:129], v[104:105], v[104:105], v[128:129]
	v_pk_fma_f32 v[128:129], v[106:107], v[106:107], v[128:129]
	v_pk_fma_f32 v[128:129], v[108:109], v[108:109], v[128:129]
	v_pk_fma_f32 v[128:129], v[110:111], v[110:111], v[128:129]
	s_nop 0
	v_add_f32_e32 v128, v128, v129
	s_waitcnt vmcnt(30)
	v_lshlrev_b32_e32 v112, 16, v64
	v_and_b32_e32 v113, 0xffff0000, v64
	v_lshlrev_b32_e32 v114, 16, v65
	v_and_b32_e32 v115, 0xffff0000, v65
	v_lshlrev_b32_e32 v116, 16, v66
	v_and_b32_e32 v117, 0xffff0000, v66
	v_lshlrev_b32_e32 v118, 16, v67
	v_and_b32_e32 v119, 0xffff0000, v67
	v_lshlrev_b32_e32 v120, 16, v68
	v_and_b32_e32 v121, 0xffff0000, v68
	v_lshlrev_b32_e32 v122, 16, v69
	v_and_b32_e32 v123, 0xffff0000, v69
	v_lshlrev_b32_e32 v124, 16, v70
	v_and_b32_e32 v125, 0xffff0000, v70
	v_lshlrev_b32_e32 v126, 16, v71
	v_and_b32_e32 v127, 0xffff0000, v71
	v_pk_mul_f32 v[130:131], v[112:113], v[112:113]
	v_pk_fma_f32 v[130:131], v[114:115], v[114:115], v[130:131]
	v_pk_fma_f32 v[130:131], v[116:117], v[116:117], v[130:131]
	v_pk_fma_f32 v[130:131], v[118:119], v[118:119], v[130:131]
	v_pk_fma_f32 v[130:131], v[120:121], v[120:121], v[130:131]
	v_pk_fma_f32 v[130:131], v[122:123], v[122:123], v[130:131]
	v_pk_fma_f32 v[130:131], v[124:125], v[124:125], v[130:131]
	v_pk_fma_f32 v[130:131], v[126:127], v[126:127], v[130:131]
	s_nop 0
	v_add_f32_e32 v130, v130, v131
	s_nop 1
	v_add_f32_dpp v128, v128, v128 quad_perm:[1,0,3,2] row_mask:0xf bank_mask:0xf
	v_add_f32_dpp v130, v130, v130 quad_perm:[1,0,3,2] row_mask:0xf bank_mask:0xf
	s_nop 0
	v_add_f32_dpp v128, v128, v128 quad_perm:[2,3,0,1] row_mask:0xf bank_mask:0xf
	v_add_f32_dpp v130, v130, v130 quad_perm:[2,3,0,1] row_mask:0xf bank_mask:0xf
	s_nop 0
	v_add_f32_dpp v128, v128, v128 row_half_mirror row_mask:0xf bank_mask:0xf
	v_add_f32_dpp v130, v130, v130 row_half_mirror row_mask:0xf bank_mask:0xf
	s_nop 0
	v_add_f32_dpp v128, v128, v128 row_mirror row_mask:0xf bank_mask:0xf
	v_add_f32_dpp v130, v130, v130 row_mirror row_mask:0xf bank_mask:0xf
	s_nop 0
	ds_bpermute_b32 v136, v187, v128
	ds_bpermute_b32 v137, v187, v130
	s_waitcnt lgkmcnt(0)
;     __device__ __forceinline__ float* out() const { return (float*)karg_in(33); }
; __device__ __forceinline__ const float* xrow_ptr(const Ctx& C, int row) { return row < MPROMPT ? C.in(0) + (size_t)row * DM : C.in(1) + (size_t)(row - MPROMPT) * DM; }
; __device__ __forceinline__ v4f ld4_bf16(const bf16* p) { const v2u w = *(const v2u*)p; return (v4f){bf_lo(w.x), bf_hi(w.x), bf_lo(w.y), bf_hi(w.y)}; }
; __device__ __forceinline__ float ssq4(v4f v) { return (v.x * v.x + v.y * v.y) + (v.z * v.z + v.w * v.w); }
; template <int R, bool BASE_F32, bool OUT_F32>
; __device__ __forceinline__ void rows_res(const Ctx& C, int m0, int stride, int mx, const float* gpost, float scale, int lane) {
;     ...
;     for (int r = 0; r < R; ++r) { mr[r] = (r == 4) ? mx : m0 + r * stride; ok[r] = (r == 4) ? (mx < M) : (mr[r] < MPROMPT); const int mm = ok[r] ? mr[r] : 0;
; #pragma unroll
;         for (int j = 0; j < 4; ++j) d[r][j] = ld4_bf16(D + (size_t)mm * DM + 4 * lane + 256 * j);
;         if (BASE_F32) { const float* x = xrow_ptr(C, mm);
; #pragma unroll
;             for (int j = 0; j < 4; ++j) b[r][j] = ld4_f32(x + 4 * lane + 256 * j);
;         } else { const float inv = C.RS()[mm];
; #pragma unroll
;             for (int j = 0; j < 4; ++j) b[r][j] = ld4_bf16(XN + (size_t)mm * DM + 4 * lane + 256 * j) * inv;
;         } }
; #pragma unroll
;     for (int r = 0; r < R; ++r) { float s = 0.f;
; #pragma unroll
;         for (int j = 0; j < 4; ++j) s += ssq4(d[r][j]);
;         r1[r] = s; }
; #pragma unroll
;     for (int r = 0; r < R; ++r) r1[r] = rsqrtf(wave_sum(r1[r]) * (1.f / DM) + EPS) * scale;
; #pragma unroll
;     for (int j = 0; j < 4; ++j) { const v4f gp = ld4_f32(gpost + 4 * lane + 256 * j);
; #pragma unroll
;         for (int r = 0; r < R; ++r) d[r][j] = b[r][j] + d[r][j] * r1[r] * gp; }
;     if (OUT_F32) { float* Y = C.out();
; #pragma unroll
;         for (int r = 0; r < R; ++r)
; #pragma unroll
;             for (int j = 0; j < 4; ++j) if (ok[r]) *(v4f*)(Y + (size_t)mr[r] * DM + 4 * lane + 256 * j) = d[r][j];
	v_add_f32_e32 v128, v128, v136
	v_add_f32_e32 v130, v130, v137
	ds_bpermute_b32 v136, v188, v128
	ds_bpermute_b32 v137, v188, v130
	s_waitcnt lgkmcnt(0)
	v_add_f32_e32 v128, v128, v136
	v_add_f32_e32 v130, v130, v137
	v_fmamk_f32 v128, v128, 0x3a800000, v138
	v_fmamk_f32 v130, v130, 0x3a800000, v138
	s_nop 0
	v_rsq_f32_e32 v128, v128
	v_rsq_f32_e32 v130, v130
	s_nop 1
	v_mul_f32_e32 v128, 0.5, v128
	v_mul_f32_e32 v130, 0.5, v130
	s_waitcnt vmcnt(26)
	v_pk_mul_f32 v[96:97], v[128:129], v[96:97] op_sel_hi:[0,1]
	v_pk_mul_f32 v[98:99], v[128:129], v[98:99] op_sel_hi:[0,1]
	v_pk_mul_f32 v[100:101], v[128:129], v[100:101] op_sel_hi:[0,1]
	v_pk_mul_f32 v[102:103], v[128:129], v[102:103] op_sel_hi:[0,1]
	v_pk_mul_f32 v[104:105], v[128:129], v[104:105] op_sel_hi:[0,1]
	v_pk_mul_f32 v[106:107], v[128:129], v[106:107] op_sel_hi:[0,1]
	v_pk_mul_f32 v[108:109], v[128:129], v[108:109] op_sel_hi:[0,1]
	v_pk_mul_f32 v[110:111], v[128:129], v[110:111] op_sel_hi:[0,1]
	v_pk_mul_f32 v[96:97], v[96:97], v[192:193]
	v_pk_mul_f32 v[98:99], v[98:99], v[194:195]
	v_pk_mul_f32 v[100:101], v[100:101], v[196:197]
	v_pk_mul_f32 v[102:103], v[102:103], v[198:199]
	v_pk_mul_f32 v[104:105], v[104:105], v[200:201]
	v_pk_mul_f32 v[106:107], v[106:107], v[202:203]
	v_pk_mul_f32 v[108:109], v[108:109], v[204:205]
	v_pk_mul_f32 v[110:111], v[110:111], v[206:207]
	v_lshlrev_b32_e32 v56, 16, v72
	v_and_b32_e32 v57, 0xffff0000, v72
	v_lshlrev_b32_e32 v58, 16, v73
	v_and_b32_e32 v59, 0xffff0000, v73
	v_lshlrev_b32_e32 v60, 16, v74
	v_and_b32_e32 v61, 0xffff0000, v74
	v_lshlrev_b32_e32 v62, 16, v75
	v_and_b32_e32 v63, 0xffff0000, v75
	v_pk_fma_f32 v[96:97], v[88:89], v[56:57], v[96:97] op_sel_hi:[0,1,1]
	v_pk_fma_f32 v[98:99], v[88:89], v[58:59], v[98:99] op_sel_hi:[0,1,1]
	v_pk_fma_f32 v[100:101], v[88:89], v[60:61], v[100:101] op_sel_hi:[0,1,1]
	v_pk_fma_f32 v[102:103], v[88:89], v[62:63], v[102:103] op_sel_hi:[0,1,1]
	v_lshlrev_b32_e32 v56, 16, v76
	v_and_b32_e32 v57, 0xffff0000, v76
	v_lshlrev_b32_e32 v58, 16, v77
	v_and_b32_e32 v59, 0xffff0000, v77
	v_lshlrev_b32_e32 v60, 16, v78
	v_and_b32_e32 v61, 0xffff0000, v78
	v_lshlrev_b32_e32 v62, 16, v79
	v_and_b32_e32 v63, 0xffff0000, v79
	v_pk_fma_f32 v[104:105], v[88:89], v[56:57], v[104:105] op_sel_hi:[0,1,1]
	v_pk_fma_f32 v[106:107], v[88:89], v[58:59], v[106:107] op_sel_hi:[0,1,1]
	v_pk_fma_f32 v[108:109], v[88:89], v[60:61], v[108:109] op_sel_hi:[0,1,1]
	v_pk_fma_f32 v[110:111], v[88:89], v[62:63], v[110:111] op_sel_hi:[0,1,1]
	global_store_dwordx4 v175, v[96:99], s[100:101]
	global_store_dwordx4 v175, v[100:103], s[100:101] offset:1024
	global_store_dwordx4 v175, v[104:107], s[100:101] offset:2048
	global_store_dwordx4 v175, v[108:111], s[100:101] offset:3072
	v_add_u32_e32 v175, 0x800000, v175
	v_pk_mul_f32 v[112:113], v[130:131], v[112:113] op_sel_hi:[0,1]
	v_pk_mul_f32 v[114:115], v[130:131], v[114:115] op_sel_hi:[0,1]
	v_pk_mul_f32 v[116:117], v[130:131], v[116:117] op_sel_hi:[0,1]
	v_pk_mul_f32 v[118:119], v[130:131], v[118:119] op_sel_hi:[0,1]
	v_pk_mul_f32 v[120:121], v[130:131], v[120:121] op_sel_hi:[0,1]
	v_pk_mul_f32 v[122:123], v[130:131], v[122:123] op_sel_hi:[0,1]
	v_pk_mul_f32 v[124:125], v[130:131], v[124:125] op_sel_hi:[0,1]
	v_pk_mul_f32 v[126:127], v[130:131], v[126:127] op_sel_hi:[0,1]
	v_pk_mul_f32 v[112:113], v[112:113], v[192:193]
	v_pk_mul_f32 v[114:115], v[114:115], v[194:195]
	v_pk_mul_f32 v[116:117], v[116:117], v[196:197]
	v_pk_mul_f32 v[118:119], v[118:119], v[198:199]
	v_pk_mul_f32 v[120:121], v[120:121], v[200:201]
	v_pk_mul_f32 v[122:123], v[122:123], v[202:203]
	v_pk_mul_f32 v[124:125], v[124:125], v[204:205]
	v_pk_mul_f32 v[126:127], v[126:127], v[206:207]
	v_lshlrev_b32_e32 v64, 16, v80
	v_and_b32_e32 v65, 0xffff0000, v80
	v_lshlrev_b32_e32 v66, 16, v81
	v_and_b32_e32 v67, 0xffff0000, v81
	v_lshlrev_b32_e32 v68, 16, v82
	v_and_b32_e32 v69, 0xffff0000, v82
	v_lshlrev_b32_e32 v70, 16, v83
	v_and_b32_e32 v71, 0xffff0000, v83
	v_pk_fma_f32 v[112:113], v[90:91], v[64:65], v[112:113] op_sel_hi:[0,1,1]
	v_pk_fma_f32 v[114:115], v[90:91], v[66:67], v[114:115] op_sel_hi:[0,1,1]
	v_pk_fma_f32 v[116:117], v[90:91], v[68:69], v[116:117] op_sel_hi:[0,1,1]
	v_pk_fma_f32 v[118:119], v[90:91], v[70:71], v[118:119] op_sel_hi:[0,1,1]
	v_lshlrev_b32_e32 v64, 16, v84
	v_and_b32_e32 v65, 0xffff0000, v84
	v_lshlrev_b32_e32 v66, 16, v85
	v_and_b32_e32 v67, 0xffff0000, v85
	v_lshlrev_b32_e32 v68, 16, v86
	v_and_b32_e32 v69, 0xffff0000, v86
	v_lshlrev_b32_e32 v70, 16, v87
	v_and_b32_e32 v71, 0xffff0000, v87
	v_pk_fma_f32 v[120:121], v[90:91], v[64:65], v[120:121] op_sel_hi:[0,1,1]
	v_pk_fma_f32 v[122:123], v[90:91], v[66:67], v[122:123] op_sel_hi:[0,1,1]
	v_pk_fma_f32 v[124:125], v[90:91], v[68:69], v[124:125] op_sel_hi:[0,1,1]
	v_pk_fma_f32 v[126:127], v[90:91], v[70:71], v[126:127] op_sel_hi:[0,1,1]
	global_store_dwordx4 v175, v[112:115], s[100:101]
	global_store_dwordx4 v175, v[116:119], s[100:101] offset:1024
	global_store_dwordx4 v175, v[120:123], s[100:101] offset:2048
	global_store_dwordx4 v175, v[124:127], s[100:101] offset:3072
	v_add_u32_e32 v175, 0x800000, v175
	global_load_dword v88, v172, s[98:99]
	global_load_dwordx2 v[56:57], v170, s[98:99]
	global_load_dwordx2 v[58:59], v170, s[98:99] offset:512
	global_load_dwordx2 v[60:61], v170, s[98:99] offset:1024
	global_load_dwordx2 v[62:63], v170, s[98:99] offset:1536
	global_load_dwordx2 v[72:73], v171, s[98:99]
	global_load_dwordx2 v[74:75], v171, s[98:99] offset:512
	global_load_dwordx2 v[76:77], v171, s[98:99] offset:1024
	global_load_dwordx2 v[78:79], v171, s[98:99] offset:1536
	v_add_u32_e32 v170, 0x400000, v170
	v_add_u32_e32 v171, 0x400000, v171
	v_add_u32_e32 v172, 0x2000, v172
	global_load_dword v90, v172, s[98:99]
	global_load_dwordx2 v[64:65], v170, s[98:99]
	global_load_dwordx2 v[66:67], v170, s[98:99] offset:512
	global_load_dwordx2 v[68:69], v170, s[98:99] offset:1024
	global_load_dwordx2 v[70:71], v170, s[98:99] offset:1536
	global_load_dwordx2 v[80:81], v171, s[98:99]
	global_load_dwordx2 v[82:83], v171, s[98:99] offset:512
	global_load_dwordx2 v[84:85], v171, s[98:99] offset:1024
	global_load_dwordx2 v[86:87], v171, s[98:99] offset:1536
	v_add_u32_e32 v170, 0x400000, v170
	v_add_u32_e32 v171, 0x400000, v171
	v_add_u32_e32 v172, 0x2000, v172
	s_waitcnt vmcnt(39)
;     __device__ __forceinline__ float* out() const { return (float*)karg_in(33); }
; __device__ __forceinline__ float ssq4(v4f v) { return (v.x * v.x + v.y * v.y) + (v.z * v.z + v.w * v.w); }
; template <int R, bool BASE_F32, bool OUT_F32>
; __device__ __forceinline__ void rows_res(const Ctx& C, int m0, int stride, int mx, const float* gpost, float scale, int lane) {
;     ...
;     for (int r = 0; r < R; ++r) { float s = 0.f;
; #pragma unroll
;         for (int j = 0; j < 4; ++j) s += ssq4(d[r][j]);
;         r1[r] = s; }
; #pragma unroll
;     for (int r = 0; r < R; ++r) r1[r] = rsqrtf(wave_sum(r1[r]) * (1.f / DM) + EPS) * scale;
; #pragma unroll
;     for (int j = 0; j < 4; ++j) { const v4f gp = ld4_f32(gpost + 4 * lane + 256 * j);
; #pragma unroll
;         for (int r = 0; r < R; ++r) d[r][j] = b[r][j] + d[r][j] * r1[r] * gp; }
;     if (OUT_F32) { float* Y = C.out();
; #pragma unroll
;         for (int r = 0; r < R; ++r)
; #pragma unroll
;             for (int j = 0; j < 4; ++j) if (ok[r]) *(v4f*)(Y + (size_t)mr[r] * DM + 4 * lane + 256 * j) = d[r][j];
	v_lshlrev_b32_e32 v96, 16, v20
	v_and_b32_e32 v97, 0xffff0000, v20
	v_lshlrev_b32_e32 v98, 16, v21
	v_and_b32_e32 v99, 0xffff0000, v21
	v_lshlrev_b32_e32 v100, 16, v22
	v_and_b32_e32 v101, 0xffff0000, v22
	v_lshlrev_b32_e32 v102, 16, v23
	v_and_b32_e32 v103, 0xffff0000, v23
	v_lshlrev_b32_e32 v104, 16, v24
	v_and_b32_e32 v105, 0xffff0000, v24
	v_lshlrev_b32_e32 v106, 16, v25
	v_and_b32_e32 v107, 0xffff0000, v25
	v_lshlrev_b32_e32 v108, 16, v26
	v_and_b32_e32 v109, 0xffff0000, v26
	v_lshlrev_b32_e32 v110, 16, v27
	v_and_b32_e32 v111, 0xffff0000, v27
	v_pk_mul_f32 v[128:129], v[96:97], v[96:97]
	v_pk_fma_f32 v[128:129], v[98:99], v[98:99], v[128:129]
	v_pk_fma_f32 v[128:129], v[100:101], v[100:101], v[128:129]
	v_pk_fma_f32 v[128:129], v[102:103], v[102:103], v[128:129]
	v_pk_fma_f32 v[128:129], v[104:105], v[104:105], v[128:129]
	v_pk_fma_f32 v[128:129], v[106:107], v[106:107], v[128:129]
	v_pk_fma_f32 v[128:129], v[108:109], v[108:109], v[128:129]
	v_pk_fma_f32 v[128:129], v[110:111], v[110:111], v[128:129]
	s_nop 0
	v_add_f32_e32 v128, v128, v129
	s_waitcnt vmcnt(30)
	v_lshlrev_b32_e32 v112, 16, v28
	v_and_b32_e32 v113, 0xffff0000, v28
	v_lshlrev_b32_e32 v114, 16, v29
	v_and_b32_e32 v115, 0xffff0000, v29
	v_lshlrev_b32_e32 v116, 16, v30
	v_and_b32_e32 v117, 0xffff0000, v30
	v_lshlrev_b32_e32 v118, 16, v31
	v_and_b32_e32 v119, 0xffff0000, v31
	v_lshlrev_b32_e32 v120, 16, v32
	v_and_b32_e32 v121, 0xffff0000, v32
	v_lshlrev_b32_e32 v122, 16, v33
	v_and_b32_e32 v123, 0xffff0000, v33
	v_lshlrev_b32_e32 v124, 16, v34
	v_and_b32_e32 v125, 0xffff0000, v34
	v_lshlrev_b32_e32 v126, 16, v35
	v_and_b32_e32 v127, 0xffff0000, v35
	v_pk_mul_f32 v[130:131], v[112:113], v[112:113]
	v_pk_fma_f32 v[130:131], v[114:115], v[114:115], v[130:131]
	v_pk_fma_f32 v[130:131], v[116:117], v[116:117], v[130:131]
	v_pk_fma_f32 v[130:131], v[118:119], v[118:119], v[130:131]
	v_pk_fma_f32 v[130:131], v[120:121], v[120:121], v[130:131]
	v_pk_fma_f32 v[130:131], v[122:123], v[122:123], v[130:131]
	v_pk_fma_f32 v[130:131], v[124:125], v[124:125], v[130:131]
	v_pk_fma_f32 v[130:131], v[126:127], v[126:127], v[130:131]
	s_nop 0
	v_add_f32_e32 v130, v130, v131
	s_nop 1
	v_add_f32_dpp v128, v128, v128 quad_perm:[1,0,3,2] row_mask:0xf bank_mask:0xf
	v_add_f32_dpp v130, v130, v130 quad_perm:[1,0,3,2] row_mask:0xf bank_mask:0xf
	s_nop 0
	v_add_f32_dpp v128, v128, v128 quad_perm:[2,3,0,1] row_mask:0xf bank_mask:0xf
	v_add_f32_dpp v130, v130, v130 quad_perm:[2,3,0,1] row_mask:0xf bank_mask:0xf
	s_nop 0
	v_add_f32_dpp v128, v128, v128 row_half_mirror row_mask:0xf bank_mask:0xf
	v_add_f32_dpp v130, v130, v130 row_half_mirror row_mask:0xf bank_mask:0xf
	s_nop 0
	v_add_f32_dpp v128, v128, v128 row_mirror row_mask:0xf bank_mask:0xf
	v_add_f32_dpp v130, v130, v130 row_mirror row_mask:0xf bank_mask:0xf
	s_nop 0
	ds_bpermute_b32 v136, v187, v128
	ds_bpermute_b32 v137, v187, v130
	s_waitcnt lgkmcnt(0)
	v_add_f32_e32 v128, v128, v136
	v_add_f32_e32 v130, v130, v137
	ds_bpermute_b32 v136, v188, v128
	ds_bpermute_b32 v137, v188, v130
	s_waitcnt lgkmcnt(0)
	v_add_f32_e32 v128, v128, v136
	v_add_f32_e32 v130, v130, v137
	v_fmamk_f32 v128, v128, 0x3a800000, v138
	v_fmamk_f32 v130, v130, 0x3a800000, v138
	s_nop 0
	v_rsq_f32_e32 v128, v128
	v_rsq_f32_e32 v130, v130
	s_nop 1
	v_mul_f32_e32 v128, 0.5, v128
	v_mul_f32_e32 v130, 0.5, v130
	s_waitcnt vmcnt(26)
	v_pk_mul_f32 v[96:97], v[128:129], v[96:97] op_sel_hi:[0,1]
	v_pk_mul_f32 v[98:99], v[128:129], v[98:99] op_sel_hi:[0,1]
	v_pk_mul_f32 v[100:101], v[128:129], v[100:101] op_sel_hi:[0,1]
	v_pk_mul_f32 v[102:103], v[128:129], v[102:103] op_sel_hi:[0,1]
	v_pk_mul_f32 v[104:105], v[128:129], v[104:105] op_sel_hi:[0,1]
	v_pk_mul_f32 v[106:107], v[128:129], v[106:107] op_sel_hi:[0,1]
	v_pk_mul_f32 v[108:109], v[128:129], v[108:109] op_sel_hi:[0,1]
	v_pk_mul_f32 v[110:111], v[128:129], v[110:111] op_sel_hi:[0,1]
	v_pk_mul_f32 v[96:97], v[96:97], v[192:193]
	v_pk_mul_f32 v[98:99], v[98:99], v[194:195]
	v_pk_mul_f32 v[100:101], v[100:101], v[196:197]
	v_pk_mul_f32 v[102:103], v[102:103], v[198:199]
	v_pk_mul_f32 v[104:105], v[104:105], v[200:201]
	v_pk_mul_f32 v[106:107], v[106:107], v[202:203]
	v_pk_mul_f32 v[108:109], v[108:109], v[204:205]
	v_pk_mul_f32 v[110:111], v[110:111], v[206:207]
	v_lshlrev_b32_e32 v20, 16, v36
	v_and_b32_e32 v21, 0xffff0000, v36
	v_lshlrev_b32_e32 v22, 16, v37
	v_and_b32_e32 v23, 0xffff0000, v37
	v_lshlrev_b32_e32 v24, 16, v38
	v_and_b32_e32 v25, 0xffff0000, v38
	v_lshlrev_b32_e32 v26, 16, v39
	v_and_b32_e32 v27, 0xffff0000, v39
	v_pk_fma_f32 v[96:97], v[52:53], v[20:21], v[96:97] op_sel_hi:[0,1,1]
	v_pk_fma_f32 v[98:99], v[52:53], v[22:23], v[98:99] op_sel_hi:[0,1,1]
	v_pk_fma_f32 v[100:101], v[52:53], v[24:25], v[100:101] op_sel_hi:[0,1,1]
	v_pk_fma_f32 v[102:103], v[52:53], v[26:27], v[102:103] op_sel_hi:[0,1,1]
	v_lshlrev_b32_e32 v20, 16, v40
	v_and_b32_e32 v21, 0xffff0000, v40
	v_lshlrev_b32_e32 v22, 16, v41
	v_and_b32_e32 v23, 0xffff0000, v41
	v_lshlrev_b32_e32 v24, 16, v42
	v_and_b32_e32 v25, 0xffff0000, v42
	v_lshlrev_b32_e32 v26, 16, v43
	v_and_b32_e32 v27, 0xffff0000, v43
	v_pk_fma_f32 v[104:105], v[52:53], v[20:21], v[104:105] op_sel_hi:[0,1,1]
	v_pk_fma_f32 v[106:107], v[52:53], v[22:23], v[106:107] op_sel_hi:[0,1,1]
	v_pk_fma_f32 v[108:109], v[52:53], v[24:25], v[108:109] op_sel_hi:[0,1,1]
	v_pk_fma_f32 v[110:111], v[52:53], v[26:27], v[110:111] op_sel_hi:[0,1,1]
	global_store_dwordx4 v175, v[96:99], s[100:101]
	global_store_dwordx4 v175, v[100:103], s[100:101] offset:1024
	global_store_dwordx4 v175, v[104:107], s[100:101] offset:2048
	global_store_dwordx4 v175, v[108:111], s[100:101] offset:3072
;     __device__ __forceinline__ float* out() const { return (float*)karg_in(33); }
; __device__ __forceinline__ const float* xrow_ptr(const Ctx& C, int row) { return row < MPROMPT ? C.in(0) + (size_t)row * DM : C.in(1) + (size_t)(row - MPROMPT) * DM; }
; __device__ __forceinline__ v4f ld4_bf16(const bf16* p) { const v2u w = *(const v2u*)p; return (v4f){bf_lo(w.x), bf_hi(w.x), bf_lo(w.y), bf_hi(w.y)}; }
; __device__ __forceinline__ float ssq4(v4f v) { return (v.x * v.x + v.y * v.y) + (v.z * v.z + v.w * v.w); }
; template <int R, bool BASE_F32, bool OUT_F32>
; __device__ __forceinline__ void rows_res(const Ctx& C, int m0, int stride, int mx, const float* gpost, float scale, int lane) {
;     ...
;     for (int r = 0; r < R; ++r) { mr[r] = (r == 4) ? mx : m0 + r * stride; ok[r] = (r == 4) ? (mx < M) : (mr[r] < MPROMPT); const int mm = ok[r] ? mr[r] : 0;
; #pragma unroll
;         for (int j = 0; j < 4; ++j) d[r][j] = ld4_bf16(D + (size_t)mm * DM + 4 * lane + 256 * j);
;         if (BASE_F32) { const float* x = xrow_ptr(C, mm);
; #pragma unroll
;             for (int j = 0; j < 4; ++j) b[r][j] = ld4_f32(x + 4 * lane + 256 * j);
;         } else { const float inv = C.RS()[mm];
; #pragma unroll
;             for (int j = 0; j < 4; ++j) b[r][j] = ld4_bf16(XN + (size_t)mm * DM + 4 * lane + 256 * j) * inv;
;         } }
; #pragma unroll
;     for (int r = 0; r < R; ++r) { float s = 0.f;
; #pragma unroll
;         for (int j = 0; j < 4; ++j) s += ssq4(d[r][j]);
;         r1[r] = s; }
; #pragma unroll
;     for (int r = 0; r < R; ++r) r1[r] = rsqrtf(wave_sum(r1[r]) * (1.f / DM) + EPS) * scale;
; #pragma unroll
;     for (int j = 0; j < 4; ++j) { const v4f gp = ld4_f32(gpost + 4 * lane + 256 * j);
; #pragma unroll
;         for (int r = 0; r < R; ++r) d[r][j] = b[r][j] + d[r][j] * r1[r] * gp; }
;     if (OUT_F32) { float* Y = C.out();
; #pragma unroll
;         for (int r = 0; r < R; ++r)
; #pragma unroll
;             for (int j = 0; j < 4; ++j) if (ok[r]) *(v4f*)(Y + (size_t)mr[r] * DM + 4 * lane + 256 * j) = d[r][j];
	v_add_u32_e32 v175, 0x800000, v175
	v_pk_mul_f32 v[112:113], v[130:131], v[112:113] op_sel_hi:[0,1]
	v_pk_mul_f32 v[114:115], v[130:131], v[114:115] op_sel_hi:[0,1]
	v_pk_mul_f32 v[116:117], v[130:131], v[116:117] op_sel_hi:[0,1]
	v_pk_mul_f32 v[118:119], v[130:131], v[118:119] op_sel_hi:[0,1]
	v_pk_mul_f32 v[120:121], v[130:131], v[120:121] op_sel_hi:[0,1]
	v_pk_mul_f32 v[122:123], v[130:131], v[122:123] op_sel_hi:[0,1]
	v_pk_mul_f32 v[124:125], v[130:131], v[124:125] op_sel_hi:[0,1]
	v_pk_mul_f32 v[126:127], v[130:131], v[126:127] op_sel_hi:[0,1]
	v_pk_mul_f32 v[112:113], v[112:113], v[192:193]
	v_pk_mul_f32 v[114:115], v[114:115], v[194:195]
	v_pk_mul_f32 v[116:117], v[116:117], v[196:197]
	v_pk_mul_f32 v[118:119], v[118:119], v[198:199]
	v_pk_mul_f32 v[120:121], v[120:121], v[200:201]
	v_pk_mul_f32 v[122:123], v[122:123], v[202:203]
	v_pk_mul_f32 v[124:125], v[124:125], v[204:205]
	v_pk_mul_f32 v[126:127], v[126:127], v[206:207]
	v_lshlrev_b32_e32 v28, 16, v44
	v_and_b32_e32 v29, 0xffff0000, v44
	v_lshlrev_b32_e32 v30, 16, v45
	v_and_b32_e32 v31, 0xffff0000, v45
	v_lshlrev_b32_e32 v32, 16, v46
	v_and_b32_e32 v33, 0xffff0000, v46
	v_lshlrev_b32_e32 v34, 16, v47
	v_and_b32_e32 v35, 0xffff0000, v47
	v_pk_fma_f32 v[112:113], v[54:55], v[28:29], v[112:113] op_sel_hi:[0,1,1]
	v_pk_fma_f32 v[114:115], v[54:55], v[30:31], v[114:115] op_sel_hi:[0,1,1]
	v_pk_fma_f32 v[116:117], v[54:55], v[32:33], v[116:117] op_sel_hi:[0,1,1]
	v_pk_fma_f32 v[118:119], v[54:55], v[34:35], v[118:119] op_sel_hi:[0,1,1]
	v_lshlrev_b32_e32 v28, 16, v48
	v_and_b32_e32 v29, 0xffff0000, v48
	v_lshlrev_b32_e32 v30, 16, v49
	v_and_b32_e32 v31, 0xffff0000, v49
	v_lshlrev_b32_e32 v32, 16, v50
	v_and_b32_e32 v33, 0xffff0000, v50
	v_lshlrev_b32_e32 v34, 16, v51
	v_and_b32_e32 v35, 0xffff0000, v51
	v_pk_fma_f32 v[120:121], v[54:55], v[28:29], v[120:121] op_sel_hi:[0,1,1]
	v_pk_fma_f32 v[122:123], v[54:55], v[30:31], v[122:123] op_sel_hi:[0,1,1]
	v_pk_fma_f32 v[124:125], v[54:55], v[32:33], v[124:125] op_sel_hi:[0,1,1]
	v_pk_fma_f32 v[126:127], v[54:55], v[34:35], v[126:127] op_sel_hi:[0,1,1]
	global_store_dwordx4 v175, v[112:115], s[100:101]
	global_store_dwordx4 v175, v[116:119], s[100:101] offset:1024
	global_store_dwordx4 v175, v[120:123], s[100:101] offset:2048
	global_store_dwordx4 v175, v[124:127], s[100:101] offset:3072
	v_add_u32_e32 v175, 0x800000, v175
	global_load_dword v52, v172, s[98:99]
	global_load_dwordx2 v[20:21], v170, s[98:99]
	global_load_dwordx2 v[22:23], v170, s[98:99] offset:512
	global_load_dwordx2 v[24:25], v170, s[98:99] offset:1024
	global_load_dwordx2 v[26:27], v170, s[98:99] offset:1536
	global_load_dwordx2 v[36:37], v171, s[98:99]
	global_load_dwordx2 v[38:39], v171, s[98:99] offset:512
	global_load_dwordx2 v[40:41], v171, s[98:99] offset:1024
	global_load_dwordx2 v[42:43], v171, s[98:99] offset:1536
	v_add_u32_e32 v170, 0x400000, v170
	v_add_u32_e32 v171, 0x400000, v171
	v_add_u32_e32 v172, 0x2000, v172
	global_load_dword v54, v172, s[98:99]
	global_load_dwordx2 v[28:29], v170, s[98:99]
	global_load_dwordx2 v[30:31], v170, s[98:99] offset:512
	global_load_dwordx2 v[32:33], v170, s[98:99] offset:1024
	global_load_dwordx2 v[34:35], v170, s[98:99] offset:1536
	global_load_dwordx2 v[44:45], v171, s[98:99]
	global_load_dwordx2 v[46:47], v171, s[98:99] offset:512
	global_load_dwordx2 v[48:49], v171, s[98:99] offset:1024
	global_load_dwordx2 v[50:51], v171, s[98:99] offset:1536
	v_add_u32_e32 v170, 0x400000, v170
	v_add_u32_e32 v171, 0x400000, v171
	v_add_u32_e32 v172, 0x2000, v172
	s_waitcnt vmcnt(39)
	v_lshlrev_b32_e32 v96, 16, v56
	v_and_b32_e32 v97, 0xffff0000, v56
	v_lshlrev_b32_e32 v98, 16, v57
	v_and_b32_e32 v99, 0xffff0000, v57
	v_lshlrev_b32_e32 v100, 16, v58
	v_and_b32_e32 v101, 0xffff0000, v58
	v_lshlrev_b32_e32 v102, 16, v59
	v_and_b32_e32 v103, 0xffff0000, v59
	v_lshlrev_b32_e32 v104, 16, v60
	v_and_b32_e32 v105, 0xffff0000, v60
	v_lshlrev_b32_e32 v106, 16, v61
	v_and_b32_e32 v107, 0xffff0000, v61
	v_lshlrev_b32_e32 v108, 16, v62
	v_and_b32_e32 v109, 0xffff0000, v62
	v_lshlrev_b32_e32 v110, 16, v63
	v_and_b32_e32 v111, 0xffff0000, v63
	v_pk_mul_f32 v[128:129], v[96:97], v[96:97]
	v_pk_fma_f32 v[128:129], v[98:99], v[98:99], v[128:129]
	v_pk_fma_f32 v[128:129], v[100:101], v[100:101], v[128:129]
	v_pk_fma_f32 v[128:129], v[102:103], v[102:103], v[128:129]
	v_pk_fma_f32 v[128:129], v[104:105], v[104:105], v[128:129]
	v_pk_fma_f32 v[128:129], v[106:107], v[106:107], v[128:129]
	v_pk_fma_f32 v[128:129], v[108:109], v[108:109], v[128:129]
	v_pk_fma_f32 v[128:129], v[110:111], v[110:111], v[128:129]
	s_nop 0
	v_add_f32_e32 v128, v128, v129
	s_waitcnt vmcnt(30)
	v_lshlrev_b32_e32 v112, 16, v64
	v_and_b32_e32 v113, 0xffff0000, v64
	v_lshlrev_b32_e32 v114, 16, v65
	v_and_b32_e32 v115, 0xffff0000, v65
	v_lshlrev_b32_e32 v116, 16, v66
	v_and_b32_e32 v117, 0xffff0000, v66
	v_lshlrev_b32_e32 v118, 16, v67
	v_and_b32_e32 v119, 0xffff0000, v67
	v_lshlrev_b32_e32 v120, 16, v68
	v_and_b32_e32 v121, 0xffff0000, v68
	v_lshlrev_b32_e32 v122, 16, v69
	v_and_b32_e32 v123, 0xffff0000, v69
	v_lshlrev_b32_e32 v124, 16, v70
	v_and_b32_e32 v125, 0xffff0000, v70
	v_lshlrev_b32_e32 v126, 16, v71
	v_and_b32_e32 v127, 0xffff0000, v71
	v_pk_mul_f32 v[130:131], v[112:113], v[112:113]
	v_pk_fma_f32 v[130:131], v[114:115], v[114:115], v[130:131]
	v_pk_fma_f32 v[130:131], v[116:117], v[116:117], v[130:131]
	v_pk_fma_f32 v[130:131], v[118:119], v[118:119], v[130:131]
	v_pk_fma_f32 v[130:131], v[120:121], v[120:121], v[130:131]
	v_pk_fma_f32 v[130:131], v[122:123], v[122:123], v[130:131]
	v_pk_fma_f32 v[130:131], v[124:125], v[124:125], v[130:131]
	v_pk_fma_f32 v[130:131], v[126:127], v[126:127], v[130:131]
	s_nop 0
	v_add_f32_e32 v130, v130, v131
	s_nop 1
	v_add_f32_dpp v128, v128, v128 quad_perm:[1,0,3,2] row_mask:0xf bank_mask:0xf
	v_add_f32_dpp v130, v130, v130 quad_perm:[1,0,3,2] row_mask:0xf bank_mask:0xf
	s_nop 0
	v_add_f32_dpp v128, v128, v128 quad_perm:[2,3,0,1] row_mask:0xf bank_mask:0xf
	v_add_f32_dpp v130, v130, v130 quad_perm:[2,3,0,1] row_mask:0xf bank_mask:0xf
	s_nop 0
	v_add_f32_dpp v128, v128, v128 row_half_mirror row_mask:0xf bank_mask:0xf
	v_add_f32_dpp v130, v130, v130 row_half_mirror row_mask:0xf bank_mask:0xf
	s_nop 0
	v_add_f32_dpp v128, v128, v128 row_mirror row_mask:0xf bank_mask:0xf
	v_add_f32_dpp v130, v130, v130 row_mirror row_mask:0xf bank_mask:0xf
	s_nop 0
	ds_bpermute_b32 v136, v187, v128
	ds_bpermute_b32 v137, v187, v130
	s_waitcnt lgkmcnt(0)
;     __device__ __forceinline__ float* out() const { return (float*)karg_in(33); }
; __device__ __forceinline__ const float* xrow_ptr(const Ctx& C, int row) { return row < MPROMPT ? C.in(0) + (size_t)row * DM : C.in(1) + (size_t)(row - MPROMPT) * DM; }
; __device__ __forceinline__ v4f ld4_bf16(const bf16* p) { const v2u w = *(const v2u*)p; return (v4f){bf_lo(w.x), bf_hi(w.x), bf_lo(w.y), bf_hi(w.y)}; }
; __device__ __forceinline__ float ssq4(v4f v) { return (v.x * v.x + v.y * v.y) + (v.z * v.z + v.w * v.w); }
; template <int R, bool BASE_F32, bool OUT_F32>
; __device__ __forceinline__ void rows_res(const Ctx& C, int m0, int stride, int mx, const float* gpost, float scale, int lane) {
;     ...
;     for (int r = 0; r < R; ++r) { mr[r] = (r == 4) ? mx : m0 + r * stride; ok[r] = (r == 4) ? (mx < M) : (mr[r] < MPROMPT); const int mm = ok[r] ? mr[r] : 0;
; #pragma unroll
;         for (int j = 0; j < 4; ++j) d[r][j] = ld4_bf16(D + (size_t)mm * DM + 4 * lane + 256 * j);
;         if (BASE_F32) { const float* x = xrow_ptr(C, mm);
; #pragma unroll
;             for (int j = 0; j < 4; ++j) b[r][j] = ld4_f32(x + 4 * lane + 256 * j);
;         } else { const float inv = C.RS()[mm];
; #pragma unroll
;             for (int j = 0; j < 4; ++j) b[r][j] = ld4_bf16(XN + (size_t)mm * DM + 4 * lane + 256 * j) * inv;
;         } }
; #pragma unroll
;     for (int r = 0; r < R; ++r) { float s = 0.f;
; #pragma unroll
;         for (int j = 0; j < 4; ++j) s += ssq4(d[r][j]);
;         r1[r] = s; }
; #pragma unroll
;     for (int r = 0; r < R; ++r) r1[r] = rsqrtf(wave_sum(r1[r]) * (1.f / DM) + EPS) * scale;
; #pragma unroll
;     for (int j = 0; j < 4; ++j) { const v4f gp = ld4_f32(gpost + 4 * lane + 256 * j);
; #pragma unroll
;         for (int r = 0; r < R; ++r) d[r][j] = b[r][j] + d[r][j] * r1[r] * gp; }
;     if (OUT_F32) { float* Y = C.out();
; #pragma unroll
;         for (int r = 0; r < R; ++r)
; #pragma unroll
;             for (int j = 0; j < 4; ++j) if (ok[r]) *(v4f*)(Y + (size_t)mr[r] * DM + 4 * lane + 256 * j) = d[r][j];
	v_add_f32_e32 v128, v128, v136
	v_add_f32_e32 v130, v130, v137
	ds_bpermute_b32 v136, v188, v128
	ds_bpermute_b32 v137, v188, v130
	s_waitcnt lgkmcnt(0)
	v_add_f32_e32 v128, v128, v136
	v_add_f32_e32 v130, v130, v137
	v_fmamk_f32 v128, v128, 0x3a800000, v138
	v_fmamk_f32 v130, v130, 0x3a800000, v138
	s_nop 0
	v_rsq_f32_e32 v128, v128
	v_rsq_f32_e32 v130, v130
	s_nop 1
	v_mul_f32_e32 v128, 0.5, v128
	v_mul_f32_e32 v130, 0.5, v130
	s_waitcnt vmcnt(26)
	v_pk_mul_f32 v[96:97], v[128:129], v[96:97] op_sel_hi:[0,1]
	v_pk_mul_f32 v[98:99], v[128:129], v[98:99] op_sel_hi:[0,1]
	v_pk_mul_f32 v[100:101], v[128:129], v[100:101] op_sel_hi:[0,1]
	v_pk_mul_f32 v[102:103], v[128:129], v[102:103] op_sel_hi:[0,1]
	v_pk_mul_f32 v[104:105], v[128:129], v[104:105] op_sel_hi:[0,1]
	v_pk_mul_f32 v[106:107], v[128:129], v[106:107] op_sel_hi:[0,1]
	v_pk_mul_f32 v[108:109], v[128:129], v[108:109] op_sel_hi:[0,1]
	v_pk_mul_f32 v[110:111], v[128:129], v[110:111] op_sel_hi:[0,1]
	v_pk_mul_f32 v[96:97], v[96:97], v[192:193]
	v_pk_mul_f32 v[98:99], v[98:99], v[194:195]
	v_pk_mul_f32 v[100:101], v[100:101], v[196:197]
	v_pk_mul_f32 v[102:103], v[102:103], v[198:199]
	v_pk_mul_f32 v[104:105], v[104:105], v[200:201]
	v_pk_mul_f32 v[106:107], v[106:107], v[202:203]
	v_pk_mul_f32 v[108:109], v[108:109], v[204:205]
	v_pk_mul_f32 v[110:111], v[110:111], v[206:207]
	v_lshlrev_b32_e32 v56, 16, v72
	v_and_b32_e32 v57, 0xffff0000, v72
	v_lshlrev_b32_e32 v58, 16, v73
	v_and_b32_e32 v59, 0xffff0000, v73
	v_lshlrev_b32_e32 v60, 16, v74
	v_and_b32_e32 v61, 0xffff0000, v74
	v_lshlrev_b32_e32 v62, 16, v75
	v_and_b32_e32 v63, 0xffff0000, v75
	v_pk_fma_f32 v[96:97], v[88:89], v[56:57], v[96:97] op_sel_hi:[0,1,1]
	v_pk_fma_f32 v[98:99], v[88:89], v[58:59], v[98:99] op_sel_hi:[0,1,1]
	v_pk_fma_f32 v[100:101], v[88:89], v[60:61], v[100:101] op_sel_hi:[0,1,1]
	v_pk_fma_f32 v[102:103], v[88:89], v[62:63], v[102:103] op_sel_hi:[0,1,1]
	v_lshlrev_b32_e32 v56, 16, v76
	v_and_b32_e32 v57, 0xffff0000, v76
	v_lshlrev_b32_e32 v58, 16, v77
	v_and_b32_e32 v59, 0xffff0000, v77
	v_lshlrev_b32_e32 v60, 16, v78
	v_and_b32_e32 v61, 0xffff0000, v78
	v_lshlrev_b32_e32 v62, 16, v79
	v_and_b32_e32 v63, 0xffff0000, v79
	v_pk_fma_f32 v[104:105], v[88:89], v[56:57], v[104:105] op_sel_hi:[0,1,1]
	v_pk_fma_f32 v[106:107], v[88:89], v[58:59], v[106:107] op_sel_hi:[0,1,1]
	v_pk_fma_f32 v[108:109], v[88:89], v[60:61], v[108:109] op_sel_hi:[0,1,1]
	v_pk_fma_f32 v[110:111], v[88:89], v[62:63], v[110:111] op_sel_hi:[0,1,1]
	global_store_dwordx4 v175, v[96:99], s[100:101]
	global_store_dwordx4 v175, v[100:103], s[100:101] offset:1024
	global_store_dwordx4 v175, v[104:107], s[100:101] offset:2048
	global_store_dwordx4 v175, v[108:111], s[100:101] offset:3072
	v_add_u32_e32 v175, 0x800000, v175
	v_pk_mul_f32 v[112:113], v[130:131], v[112:113] op_sel_hi:[0,1]
	v_pk_mul_f32 v[114:115], v[130:131], v[114:115] op_sel_hi:[0,1]
	v_pk_mul_f32 v[116:117], v[130:131], v[116:117] op_sel_hi:[0,1]
	v_pk_mul_f32 v[118:119], v[130:131], v[118:119] op_sel_hi:[0,1]
	v_pk_mul_f32 v[120:121], v[130:131], v[120:121] op_sel_hi:[0,1]
	v_pk_mul_f32 v[122:123], v[130:131], v[122:123] op_sel_hi:[0,1]
	v_pk_mul_f32 v[124:125], v[130:131], v[124:125] op_sel_hi:[0,1]
	v_pk_mul_f32 v[126:127], v[130:131], v[126:127] op_sel_hi:[0,1]
	v_pk_mul_f32 v[112:113], v[112:113], v[192:193]
	v_pk_mul_f32 v[114:115], v[114:115], v[194:195]
	v_pk_mul_f32 v[116:117], v[116:117], v[196:197]
	v_pk_mul_f32 v[118:119], v[118:119], v[198:199]
	v_pk_mul_f32 v[120:121], v[120:121], v[200:201]
	v_pk_mul_f32 v[122:123], v[122:123], v[202:203]
	v_pk_mul_f32 v[124:125], v[124:125], v[204:205]
	v_pk_mul_f32 v[126:127], v[126:127], v[206:207]
	v_lshlrev_b32_e32 v64, 16, v80
	v_and_b32_e32 v65, 0xffff0000, v80
	v_lshlrev_b32_e32 v66, 16, v81
	v_and_b32_e32 v67, 0xffff0000, v81
	v_lshlrev_b32_e32 v68, 16, v82
	v_and_b32_e32 v69, 0xffff0000, v82
	v_lshlrev_b32_e32 v70, 16, v83
	v_and_b32_e32 v71, 0xffff0000, v83
	v_pk_fma_f32 v[112:113], v[90:91], v[64:65], v[112:113] op_sel_hi:[0,1,1]
	v_pk_fma_f32 v[114:115], v[90:91], v[66:67], v[114:115] op_sel_hi:[0,1,1]
	v_pk_fma_f32 v[116:117], v[90:91], v[68:69], v[116:117] op_sel_hi:[0,1,1]
	v_pk_fma_f32 v[118:119], v[90:91], v[70:71], v[118:119] op_sel_hi:[0,1,1]
	v_lshlrev_b32_e32 v64, 16, v84
	v_and_b32_e32 v65, 0xffff0000, v84
	v_lshlrev_b32_e32 v66, 16, v85
	v_and_b32_e32 v67, 0xffff0000, v85
	v_lshlrev_b32_e32 v68, 16, v86
	v_and_b32_e32 v69, 0xffff0000, v86
	v_lshlrev_b32_e32 v70, 16, v87
	v_and_b32_e32 v71, 0xffff0000, v87
	v_pk_fma_f32 v[120:121], v[90:91], v[64:65], v[120:121] op_sel_hi:[0,1,1]
	v_pk_fma_f32 v[122:123], v[90:91], v[66:67], v[122:123] op_sel_hi:[0,1,1]
	v_pk_fma_f32 v[124:125], v[90:91], v[68:69], v[124:125] op_sel_hi:[0,1,1]
	v_pk_fma_f32 v[126:127], v[90:91], v[70:71], v[126:127] op_sel_hi:[0,1,1]
	global_store_dwordx4 v175, v[112:115], s[100:101]
	global_store_dwordx4 v175, v[116:119], s[100:101] offset:1024
	global_store_dwordx4 v175, v[120:123], s[100:101] offset:2048
	global_store_dwordx4 v175, v[124:127], s[100:101] offset:3072
	v_add_u32_e32 v175, 0x800000, v175
	global_load_dword v88, v172, s[98:99]
	global_load_dwordx2 v[56:57], v170, s[98:99]
	global_load_dwordx2 v[58:59], v170, s[98:99] offset:512
	global_load_dwordx2 v[60:61], v170, s[98:99] offset:1024
	global_load_dwordx2 v[62:63], v170, s[98:99] offset:1536
	global_load_dwordx2 v[72:73], v171, s[98:99]
	global_load_dwordx2 v[74:75], v171, s[98:99] offset:512
	global_load_dwordx2 v[76:77], v171, s[98:99] offset:1024
	global_load_dwordx2 v[78:79], v171, s[98:99] offset:1536
	v_add_u32_e32 v170, 0x400000, v170
	v_add_u32_e32 v171, 0x400000, v171
	v_add_u32_e32 v172, 0x2000, v172
	global_load_dword v90, v172, s[98:99]
	global_load_dwordx2 v[64:65], v170, s[98:99]
	global_load_dwordx2 v[66:67], v170, s[98:99] offset:512
	global_load_dwordx2 v[68:69], v170, s[98:99] offset:1024
	global_load_dwordx2 v[70:71], v170, s[98:99] offset:1536
	global_load_dwordx2 v[80:81], v171, s[98:99]
	global_load_dwordx2 v[82:83], v171, s[98:99] offset:512
	global_load_dwordx2 v[84:85], v171, s[98:99] offset:1024
	global_load_dwordx2 v[86:87], v171, s[98:99] offset:1536
	v_add_u32_e32 v170, 0x400000, v170
	v_add_u32_e32 v171, 0x400000, v171
	v_add_u32_e32 v172, 0x2000, v172
	s_waitcnt vmcnt(39)
;     __device__ __forceinline__ float* out() const { return (float*)karg_in(33); }
; __device__ __forceinline__ float ssq4(v4f v) { return (v.x * v.x + v.y * v.y) + (v.z * v.z + v.w * v.w); }
; template <int R, bool BASE_F32, bool OUT_F32>
; __device__ __forceinline__ void rows_res(const Ctx& C, int m0, int stride, int mx, const float* gpost, float scale, int lane) {
;     ...
;     for (int r = 0; r < R; ++r) { float s = 0.f;
; #pragma unroll
;         for (int j = 0; j < 4; ++j) s += ssq4(d[r][j]);
;         r1[r] = s; }
; #pragma unroll
;     for (int r = 0; r < R; ++r) r1[r] = rsqrtf(wave_sum(r1[r]) * (1.f / DM) + EPS) * scale;
; #pragma unroll
;     for (int j = 0; j < 4; ++j) { const v4f gp = ld4_f32(gpost + 4 * lane + 256 * j);
; #pragma unroll
;         for (int r = 0; r < R; ++r) d[r][j] = b[r][j] + d[r][j] * r1[r] * gp; }
;     if (OUT_F32) { float* Y = C.out();
; #pragma unroll
;         for (int r = 0; r < R; ++r)
; #pragma unroll
;             for (int j = 0; j < 4; ++j) if (ok[r]) *(v4f*)(Y + (size_t)mr[r] * DM + 4 * lane + 256 * j) = d[r][j];
	v_lshlrev_b32_e32 v96, 16, v20
	v_and_b32_e32 v97, 0xffff0000, v20
	v_lshlrev_b32_e32 v98, 16, v21
	v_and_b32_e32 v99, 0xffff0000, v21
	v_lshlrev_b32_e32 v100, 16, v22
	v_and_b32_e32 v101, 0xffff0000, v22
	v_lshlrev_b32_e32 v102, 16, v23
	v_and_b32_e32 v103, 0xffff0000, v23
	v_lshlrev_b32_e32 v104, 16, v24
	v_and_b32_e32 v105, 0xffff0000, v24
	v_lshlrev_b32_e32 v106, 16, v25
	v_and_b32_e32 v107, 0xffff0000, v25
	v_lshlrev_b32_e32 v108, 16, v26
	v_and_b32_e32 v109, 0xffff0000, v26
	v_lshlrev_b32_e32 v110, 16, v27
	v_and_b32_e32 v111, 0xffff0000, v27
	v_pk_mul_f32 v[128:129], v[96:97], v[96:97]
	v_pk_fma_f32 v[128:129], v[98:99], v[98:99], v[128:129]
	v_pk_fma_f32 v[128:129], v[100:101], v[100:101], v[128:129]
	v_pk_fma_f32 v[128:129], v[102:103], v[102:103], v[128:129]
	v_pk_fma_f32 v[128:129], v[104:105], v[104:105], v[128:129]
	v_pk_fma_f32 v[128:129], v[106:107], v[106:107], v[128:129]
	v_pk_fma_f32 v[128:129], v[108:109], v[108:109], v[128:129]
	v_pk_fma_f32 v[128:129], v[110:111], v[110:111], v[128:129]
	s_nop 0
	v_add_f32_e32 v128, v128, v129
	s_waitcnt vmcnt(30)
	v_lshlrev_b32_e32 v112, 16, v28
	v_and_b32_e32 v113, 0xffff0000, v28
	v_lshlrev_b32_e32 v114, 16, v29
	v_and_b32_e32 v115, 0xffff0000, v29
	v_lshlrev_b32_e32 v116, 16, v30
	v_and_b32_e32 v117, 0xffff0000, v30
	v_lshlrev_b32_e32 v118, 16, v31
	v_and_b32_e32 v119, 0xffff0000, v31
	v_lshlrev_b32_e32 v120, 16, v32
	v_and_b32_e32 v121, 0xffff0000, v32
	v_lshlrev_b32_e32 v122, 16, v33
	v_and_b32_e32 v123, 0xffff0000, v33
	v_lshlrev_b32_e32 v124, 16, v34
	v_and_b32_e32 v125, 0xffff0000, v34
	v_lshlrev_b32_e32 v126, 16, v35
	v_and_b32_e32 v127, 0xffff0000, v35
	v_pk_mul_f32 v[130:131], v[112:113], v[112:113]
	v_pk_fma_f32 v[130:131], v[114:115], v[114:115], v[130:131]
	v_pk_fma_f32 v[130:131], v[116:117], v[116:117], v[130:131]
	v_pk_fma_f32 v[130:131], v[118:119], v[118:119], v[130:131]
	v_pk_fma_f32 v[130:131], v[120:121], v[120:121], v[130:131]
	v_pk_fma_f32 v[130:131], v[122:123], v[122:123], v[130:131]
	v_pk_fma_f32 v[130:131], v[124:125], v[124:125], v[130:131]
	v_pk_fma_f32 v[130:131], v[126:127], v[126:127], v[130:131]
	s_nop 0
	v_add_f32_e32 v130, v130, v131
	s_nop 1
	v_add_f32_dpp v128, v128, v128 quad_perm:[1,0,3,2] row_mask:0xf bank_mask:0xf
	v_add_f32_dpp v130, v130, v130 quad_perm:[1,0,3,2] row_mask:0xf bank_mask:0xf
	s_nop 0
	v_add_f32_dpp v128, v128, v128 quad_perm:[2,3,0,1] row_mask:0xf bank_mask:0xf
	v_add_f32_dpp v130, v130, v130 quad_perm:[2,3,0,1] row_mask:0xf bank_mask:0xf
	s_nop 0
	v_add_f32_dpp v128, v128, v128 row_half_mirror row_mask:0xf bank_mask:0xf
	v_add_f32_dpp v130, v130, v130 row_half_mirror row_mask:0xf bank_mask:0xf
	s_nop 0
	v_add_f32_dpp v128, v128, v128 row_mirror row_mask:0xf bank_mask:0xf
	v_add_f32_dpp v130, v130, v130 row_mirror row_mask:0xf bank_mask:0xf
	s_nop 0
	ds_bpermute_b32 v136, v187, v128
	ds_bpermute_b32 v137, v187, v130
	s_waitcnt lgkmcnt(0)
	v_add_f32_e32 v128, v128, v136
	v_add_f32_e32 v130, v130, v137
	ds_bpermute_b32 v136, v188, v128
	ds_bpermute_b32 v137, v188, v130
	s_waitcnt lgkmcnt(0)
	v_add_f32_e32 v128, v128, v136
	v_add_f32_e32 v130, v130, v137
	v_fmamk_f32 v128, v128, 0x3a800000, v138
	v_fmamk_f32 v130, v130, 0x3a800000, v138
	s_nop 0
	v_rsq_f32_e32 v128, v128
	v_rsq_f32_e32 v130, v130
	s_nop 1
	v_mul_f32_e32 v128, 0.5, v128
	v_mul_f32_e32 v130, 0.5, v130
	s_waitcnt vmcnt(26)
	v_pk_mul_f32 v[96:97], v[128:129], v[96:97] op_sel_hi:[0,1]
	v_pk_mul_f32 v[98:99], v[128:129], v[98:99] op_sel_hi:[0,1]
	v_pk_mul_f32 v[100:101], v[128:129], v[100:101] op_sel_hi:[0,1]
	v_pk_mul_f32 v[102:103], v[128:129], v[102:103] op_sel_hi:[0,1]
	v_pk_mul_f32 v[104:105], v[128:129], v[104:105] op_sel_hi:[0,1]
	v_pk_mul_f32 v[106:107], v[128:129], v[106:107] op_sel_hi:[0,1]
	v_pk_mul_f32 v[108:109], v[128:129], v[108:109] op_sel_hi:[0,1]
	v_pk_mul_f32 v[110:111], v[128:129], v[110:111] op_sel_hi:[0,1]
	v_pk_mul_f32 v[96:97], v[96:97], v[192:193]
	v_pk_mul_f32 v[98:99], v[98:99], v[194:195]
	v_pk_mul_f32 v[100:101], v[100:101], v[196:197]
	v_pk_mul_f32 v[102:103], v[102:103], v[198:199]
	v_pk_mul_f32 v[104:105], v[104:105], v[200:201]
	v_pk_mul_f32 v[106:107], v[106:107], v[202:203]
	v_pk_mul_f32 v[108:109], v[108:109], v[204:205]
	v_pk_mul_f32 v[110:111], v[110:111], v[206:207]
	v_lshlrev_b32_e32 v20, 16, v36
	v_and_b32_e32 v21, 0xffff0000, v36
	v_lshlrev_b32_e32 v22, 16, v37
	v_and_b32_e32 v23, 0xffff0000, v37
	v_lshlrev_b32_e32 v24, 16, v38
	v_and_b32_e32 v25, 0xffff0000, v38
	v_lshlrev_b32_e32 v26, 16, v39
	v_and_b32_e32 v27, 0xffff0000, v39
	v_pk_fma_f32 v[96:97], v[52:53], v[20:21], v[96:97] op_sel_hi:[0,1,1]
	v_pk_fma_f32 v[98:99], v[52:53], v[22:23], v[98:99] op_sel_hi:[0,1,1]
	v_pk_fma_f32 v[100:101], v[52:53], v[24:25], v[100:101] op_sel_hi:[0,1,1]
	v_pk_fma_f32 v[102:103], v[52:53], v[26:27], v[102:103] op_sel_hi:[0,1,1]
	v_lshlrev_b32_e32 v20, 16, v40
	v_and_b32_e32 v21, 0xffff0000, v40
	v_lshlrev_b32_e32 v22, 16, v41
	v_and_b32_e32 v23, 0xffff0000, v41
	v_lshlrev_b32_e32 v24, 16, v42
	v_and_b32_e32 v25, 0xffff0000, v42
	v_lshlrev_b32_e32 v26, 16, v43
	v_and_b32_e32 v27, 0xffff0000, v43
	v_pk_fma_f32 v[104:105], v[52:53], v[20:21], v[104:105] op_sel_hi:[0,1,1]
	v_pk_fma_f32 v[106:107], v[52:53], v[22:23], v[106:107] op_sel_hi:[0,1,1]
	v_pk_fma_f32 v[108:109], v[52:53], v[24:25], v[108:109] op_sel_hi:[0,1,1]
	v_pk_fma_f32 v[110:111], v[52:53], v[26:27], v[110:111] op_sel_hi:[0,1,1]
	global_store_dwordx4 v175, v[96:99], s[100:101]
	global_store_dwordx4 v175, v[100:103], s[100:101] offset:1024
	global_store_dwordx4 v175, v[104:107], s[100:101] offset:2048
	global_store_dwordx4 v175, v[108:111], s[100:101] offset:3072
;     __device__ __forceinline__ float* out() const { return (float*)karg_in(33); }
; __device__ __forceinline__ const float* xrow_ptr(const Ctx& C, int row) { return row < MPROMPT ? C.in(0) + (size_t)row * DM : C.in(1) + (size_t)(row - MPROMPT) * DM; }
; __device__ __forceinline__ v4f ld4_bf16(const bf16* p) { const v2u w = *(const v2u*)p; return (v4f){bf_lo(w.x), bf_hi(w.x), bf_lo(w.y), bf_hi(w.y)}; }
; __device__ __forceinline__ float ssq4(v4f v) { return (v.x * v.x + v.y * v.y) + (v.z * v.z + v.w * v.w); }
; template <int R, bool BASE_F32, bool OUT_F32>
; __device__ __forceinline__ void rows_res(const Ctx& C, int m0, int stride, int mx, const float* gpost, float scale, int lane) {
;     ...
;     for (int r = 0; r < R; ++r) { mr[r] = (r == 4) ? mx : m0 + r * stride; ok[r] = (r == 4) ? (mx < M) : (mr[r] < MPROMPT); const int mm = ok[r] ? mr[r] : 0;
; #pragma unroll
;         for (int j = 0; j < 4; ++j) d[r][j] = ld4_bf16(D + (size_t)mm * DM + 4 * lane + 256 * j);
;         if (BASE_F32) { const float* x = xrow_ptr(C, mm);
; #pragma unroll
;             for (int j = 0; j < 4; ++j) b[r][j] = ld4_f32(x + 4 * lane + 256 * j);
;         } else { const float inv = C.RS()[mm];
; #pragma unroll
;             for (int j = 0; j < 4; ++j) b[r][j] = ld4_bf16(XN + (size_t)mm * DM + 4 * lane + 256 * j) * inv;
;         } }
; #pragma unroll
;     for (int r = 0; r < R; ++r) { float s = 0.f;
; #pragma unroll
;         for (int j = 0; j < 4; ++j) s += ssq4(d[r][j]);
;         r1[r] = s; }
; #pragma unroll
;     for (int r = 0; r < R; ++r) r1[r] = rsqrtf(wave_sum(r1[r]) * (1.f / DM) + EPS) * scale;
; #pragma unroll
;     for (int j = 0; j < 4; ++j) { const v4f gp = ld4_f32(gpost + 4 * lane + 256 * j);
; #pragma unroll
;         for (int r = 0; r < R; ++r) d[r][j] = b[r][j] + d[r][j] * r1[r] * gp; }
;     if (OUT_F32) { float* Y = C.out();
; #pragma unroll
;         for (int r = 0; r < R; ++r)
; #pragma unroll
;             for (int j = 0; j < 4; ++j) if (ok[r]) *(v4f*)(Y + (size_t)mr[r] * DM + 4 * lane + 256 * j) = d[r][j];
	v_add_u32_e32 v175, 0x800000, v175
	v_pk_mul_f32 v[112:113], v[130:131], v[112:113] op_sel_hi:[0,1]
	v_pk_mul_f32 v[114:115], v[130:131], v[114:115] op_sel_hi:[0,1]
	v_pk_mul_f32 v[116:117], v[130:131], v[116:117] op_sel_hi:[0,1]
	v_pk_mul_f32 v[118:119], v[130:131], v[118:119] op_sel_hi:[0,1]
	v_pk_mul_f32 v[120:121], v[130:131], v[120:121] op_sel_hi:[0,1]
	v_pk_mul_f32 v[122:123], v[130:131], v[122:123] op_sel_hi:[0,1]
	v_pk_mul_f32 v[124:125], v[130:131], v[124:125] op_sel_hi:[0,1]
	v_pk_mul_f32 v[126:127], v[130:131], v[126:127] op_sel_hi:[0,1]
	v_pk_mul_f32 v[112:113], v[112:113], v[192:193]
	v_pk_mul_f32 v[114:115], v[114:115], v[194:195]
	v_pk_mul_f32 v[116:117], v[116:117], v[196:197]
	v_pk_mul_f32 v[118:119], v[118:119], v[198:199]
	v_pk_mul_f32 v[120:121], v[120:121], v[200:201]
	v_pk_mul_f32 v[122:123], v[122:123], v[202:203]
	v_pk_mul_f32 v[124:125], v[124:125], v[204:205]
	v_pk_mul_f32 v[126:127], v[126:127], v[206:207]
	v_lshlrev_b32_e32 v28, 16, v44
	v_and_b32_e32 v29, 0xffff0000, v44
	v_lshlrev_b32_e32 v30, 16, v45
	v_and_b32_e32 v31, 0xffff0000, v45
	v_lshlrev_b32_e32 v32, 16, v46
	v_and_b32_e32 v33, 0xffff0000, v46
	v_lshlrev_b32_e32 v34, 16, v47
	v_and_b32_e32 v35, 0xffff0000, v47
	v_pk_fma_f32 v[112:113], v[54:55], v[28:29], v[112:113] op_sel_hi:[0,1,1]
	v_pk_fma_f32 v[114:115], v[54:55], v[30:31], v[114:115] op_sel_hi:[0,1,1]
	v_pk_fma_f32 v[116:117], v[54:55], v[32:33], v[116:117] op_sel_hi:[0,1,1]
	v_pk_fma_f32 v[118:119], v[54:55], v[34:35], v[118:119] op_sel_hi:[0,1,1]
	v_lshlrev_b32_e32 v28, 16, v48
	v_and_b32_e32 v29, 0xffff0000, v48
	v_lshlrev_b32_e32 v30, 16, v49
	v_and_b32_e32 v31, 0xffff0000, v49
	v_lshlrev_b32_e32 v32, 16, v50
	v_and_b32_e32 v33, 0xffff0000, v50
	v_lshlrev_b32_e32 v34, 16, v51
	v_and_b32_e32 v35, 0xffff0000, v51
	v_pk_fma_f32 v[120:121], v[54:55], v[28:29], v[120:121] op_sel_hi:[0,1,1]
	v_pk_fma_f32 v[122:123], v[54:55], v[30:31], v[122:123] op_sel_hi:[0,1,1]
	v_pk_fma_f32 v[124:125], v[54:55], v[32:33], v[124:125] op_sel_hi:[0,1,1]
	v_pk_fma_f32 v[126:127], v[54:55], v[34:35], v[126:127] op_sel_hi:[0,1,1]
	global_store_dwordx4 v175, v[112:115], s[100:101]
	global_store_dwordx4 v175, v[116:119], s[100:101] offset:1024
	global_store_dwordx4 v175, v[120:123], s[100:101] offset:2048
	global_store_dwordx4 v175, v[124:127], s[100:101] offset:3072
	v_add_u32_e32 v175, 0x800000, v175
	global_load_dword v52, v172, s[98:99]
	global_load_dwordx2 v[20:21], v170, s[98:99]
	global_load_dwordx2 v[22:23], v170, s[98:99] offset:512
	global_load_dwordx2 v[24:25], v170, s[98:99] offset:1024
	global_load_dwordx2 v[26:27], v170, s[98:99] offset:1536
	global_load_dwordx2 v[36:37], v171, s[98:99]
	global_load_dwordx2 v[38:39], v171, s[98:99] offset:512
	global_load_dwordx2 v[40:41], v171, s[98:99] offset:1024
	global_load_dwordx2 v[42:43], v171, s[98:99] offset:1536
	v_add_u32_e32 v170, 0x400000, v170
	v_add_u32_e32 v171, 0x400000, v171
	v_add_u32_e32 v172, 0x2000, v172
	s_waitcnt vmcnt(30)
	v_lshlrev_b32_e32 v96, 16, v56
	v_and_b32_e32 v97, 0xffff0000, v56
	v_lshlrev_b32_e32 v98, 16, v57
	v_and_b32_e32 v99, 0xffff0000, v57
	v_lshlrev_b32_e32 v100, 16, v58
	v_and_b32_e32 v101, 0xffff0000, v58
	v_lshlrev_b32_e32 v102, 16, v59
	v_and_b32_e32 v103, 0xffff0000, v59
	v_lshlrev_b32_e32 v104, 16, v60
	v_and_b32_e32 v105, 0xffff0000, v60
	v_lshlrev_b32_e32 v106, 16, v61
	v_and_b32_e32 v107, 0xffff0000, v61
	v_lshlrev_b32_e32 v108, 16, v62
	v_and_b32_e32 v109, 0xffff0000, v62
	v_lshlrev_b32_e32 v110, 16, v63
	v_and_b32_e32 v111, 0xffff0000, v63
	v_pk_mul_f32 v[128:129], v[96:97], v[96:97]
	v_pk_fma_f32 v[128:129], v[98:99], v[98:99], v[128:129]
	v_pk_fma_f32 v[128:129], v[100:101], v[100:101], v[128:129]
	v_pk_fma_f32 v[128:129], v[102:103], v[102:103], v[128:129]
	v_pk_fma_f32 v[128:129], v[104:105], v[104:105], v[128:129]
	v_pk_fma_f32 v[128:129], v[106:107], v[106:107], v[128:129]
	v_pk_fma_f32 v[128:129], v[108:109], v[108:109], v[128:129]
	v_pk_fma_f32 v[128:129], v[110:111], v[110:111], v[128:129]
	s_nop 0
	v_add_f32_e32 v128, v128, v129
	s_waitcnt vmcnt(21)
	v_lshlrev_b32_e32 v112, 16, v64
	v_and_b32_e32 v113, 0xffff0000, v64
	v_lshlrev_b32_e32 v114, 16, v65
	v_and_b32_e32 v115, 0xffff0000, v65
	v_lshlrev_b32_e32 v116, 16, v66
	v_and_b32_e32 v117, 0xffff0000, v66
	v_lshlrev_b32_e32 v118, 16, v67
	v_and_b32_e32 v119, 0xffff0000, v67
	v_lshlrev_b32_e32 v120, 16, v68
	v_and_b32_e32 v121, 0xffff0000, v68
	v_lshlrev_b32_e32 v122, 16, v69
	v_and_b32_e32 v123, 0xffff0000, v69
	v_lshlrev_b32_e32 v124, 16, v70
	v_and_b32_e32 v125, 0xffff0000, v70
	v_lshlrev_b32_e32 v126, 16, v71
	v_and_b32_e32 v127, 0xffff0000, v71
	v_pk_mul_f32 v[130:131], v[112:113], v[112:113]
	v_pk_fma_f32 v[130:131], v[114:115], v[114:115], v[130:131]
	v_pk_fma_f32 v[130:131], v[116:117], v[116:117], v[130:131]
	v_pk_fma_f32 v[130:131], v[118:119], v[118:119], v[130:131]
	v_pk_fma_f32 v[130:131], v[120:121], v[120:121], v[130:131]
	v_pk_fma_f32 v[130:131], v[122:123], v[122:123], v[130:131]
	v_pk_fma_f32 v[130:131], v[124:125], v[124:125], v[130:131]
	v_pk_fma_f32 v[130:131], v[126:127], v[126:127], v[130:131]
	s_nop 0
	v_add_f32_e32 v130, v130, v131
	s_nop 1
	v_add_f32_dpp v128, v128, v128 quad_perm:[1,0,3,2] row_mask:0xf bank_mask:0xf
	v_add_f32_dpp v130, v130, v130 quad_perm:[1,0,3,2] row_mask:0xf bank_mask:0xf
	s_nop 0
	v_add_f32_dpp v128, v128, v128 quad_perm:[2,3,0,1] row_mask:0xf bank_mask:0xf
	v_add_f32_dpp v130, v130, v130 quad_perm:[2,3,0,1] row_mask:0xf bank_mask:0xf
	s_nop 0
	v_add_f32_dpp v128, v128, v128 row_half_mirror row_mask:0xf bank_mask:0xf
	v_add_f32_dpp v130, v130, v130 row_half_mirror row_mask:0xf bank_mask:0xf
	s_nop 0
	v_add_f32_dpp v128, v128, v128 row_mirror row_mask:0xf bank_mask:0xf
	v_add_f32_dpp v130, v130, v130 row_mirror row_mask:0xf bank_mask:0xf
	s_nop 0
	ds_bpermute_b32 v136, v187, v128
	ds_bpermute_b32 v137, v187, v130
	s_waitcnt lgkmcnt(0)
;     __device__ __forceinline__ float* out() const { return (float*)karg_in(33); }
; template <int R, bool BASE_F32, bool OUT_F32>
; __device__ __forceinline__ void rows_res(const Ctx& C, int m0, int stride, int mx, const float* gpost, float scale, int lane) {
;     ...
;     for (int r = 0; r < R; ++r) r1[r] = rsqrtf(wave_sum(r1[r]) * (1.f / DM) + EPS) * scale;
; #pragma unroll
;     for (int j = 0; j < 4; ++j) { const v4f gp = ld4_f32(gpost + 4 * lane + 256 * j);
; #pragma unroll
;         for (int r = 0; r < R; ++r) d[r][j] = b[r][j] + d[r][j] * r1[r] * gp; }
;     if (OUT_F32) { float* Y = C.out();
; #pragma unroll
;         for (int r = 0; r < R; ++r)
; #pragma unroll
;             for (int j = 0; j < 4; ++j) if (ok[r]) *(v4f*)(Y + (size_t)mr[r] * DM + 4 * lane + 256 * j) = d[r][j];
	v_add_f32_e32 v128, v128, v136
	v_add_f32_e32 v130, v130, v137
	ds_bpermute_b32 v136, v188, v128
	ds_bpermute_b32 v137, v188, v130
	s_waitcnt lgkmcnt(0)
	v_add_f32_e32 v128, v128, v136
	v_add_f32_e32 v130, v130, v137
	v_fmamk_f32 v128, v128, 0x3a800000, v138
	v_fmamk_f32 v130, v130, 0x3a800000, v138
	s_nop 0
	v_rsq_f32_e32 v128, v128
	v_rsq_f32_e32 v130, v130
	s_nop 1
	v_mul_f32_e32 v128, 0.5, v128
	v_mul_f32_e32 v130, 0.5, v130
	s_waitcnt vmcnt(17)
	v_pk_mul_f32 v[96:97], v[128:129], v[96:97] op_sel_hi:[0,1]
	v_pk_mul_f32 v[98:99], v[128:129], v[98:99] op_sel_hi:[0,1]
	v_pk_mul_f32 v[100:101], v[128:129], v[100:101] op_sel_hi:[0,1]
	v_pk_mul_f32 v[102:103], v[128:129], v[102:103] op_sel_hi:[0,1]
	v_pk_mul_f32 v[104:105], v[128:129], v[104:105] op_sel_hi:[0,1]
	v_pk_mul_f32 v[106:107], v[128:129], v[106:107] op_sel_hi:[0,1]
	v_pk_mul_f32 v[108:109], v[128:129], v[108:109] op_sel_hi:[0,1]
	v_pk_mul_f32 v[110:111], v[128:129], v[110:111] op_sel_hi:[0,1]
	v_pk_mul_f32 v[96:97], v[96:97], v[192:193]
	v_pk_mul_f32 v[98:99], v[98:99], v[194:195]
	v_pk_mul_f32 v[100:101], v[100:101], v[196:197]
	v_pk_mul_f32 v[102:103], v[102:103], v[198:199]
	v_pk_mul_f32 v[104:105], v[104:105], v[200:201]
	v_pk_mul_f32 v[106:107], v[106:107], v[202:203]
	v_pk_mul_f32 v[108:109], v[108:109], v[204:205]
	v_pk_mul_f32 v[110:111], v[110:111], v[206:207]
	v_lshlrev_b32_e32 v56, 16, v72
	v_and_b32_e32 v57, 0xffff0000, v72
	v_lshlrev_b32_e32 v58, 16, v73
	v_and_b32_e32 v59, 0xffff0000, v73
	v_lshlrev_b32_e32 v60, 16, v74
	v_and_b32_e32 v61, 0xffff0000, v74
	v_lshlrev_b32_e32 v62, 16, v75
	v_and_b32_e32 v63, 0xffff0000, v75
	v_pk_fma_f32 v[96:97], v[88:89], v[56:57], v[96:97] op_sel_hi:[0,1,1]
	v_pk_fma_f32 v[98:99], v[88:89], v[58:59], v[98:99] op_sel_hi:[0,1,1]
	v_pk_fma_f32 v[100:101], v[88:89], v[60:61], v[100:101] op_sel_hi:[0,1,1]
	v_pk_fma_f32 v[102:103], v[88:89], v[62:63], v[102:103] op_sel_hi:[0,1,1]
	v_lshlrev_b32_e32 v56, 16, v76
	v_and_b32_e32 v57, 0xffff0000, v76
	v_lshlrev_b32_e32 v58, 16, v77
	v_and_b32_e32 v59, 0xffff0000, v77
	v_lshlrev_b32_e32 v60, 16, v78
	v_and_b32_e32 v61, 0xffff0000, v78
	v_lshlrev_b32_e32 v62, 16, v79
	v_and_b32_e32 v63, 0xffff0000, v79
	v_pk_fma_f32 v[104:105], v[88:89], v[56:57], v[104:105] op_sel_hi:[0,1,1]
	v_pk_fma_f32 v[106:107], v[88:89], v[58:59], v[106:107] op_sel_hi:[0,1,1]
	v_pk_fma_f32 v[108:109], v[88:89], v[60:61], v[108:109] op_sel_hi:[0,1,1]
	v_pk_fma_f32 v[110:111], v[88:89], v[62:63], v[110:111] op_sel_hi:[0,1,1]
	global_store_dwordx4 v175, v[96:99], s[100:101]
	global_store_dwordx4 v175, v[100:103], s[100:101] offset:1024
	global_store_dwordx4 v175, v[104:107], s[100:101] offset:2048
	global_store_dwordx4 v175, v[108:111], s[100:101] offset:3072
	v_add_u32_e32 v175, 0x800000, v175
	v_pk_mul_f32 v[112:113], v[130:131], v[112:113] op_sel_hi:[0,1]
	v_pk_mul_f32 v[114:115], v[130:131], v[114:115] op_sel_hi:[0,1]
	v_pk_mul_f32 v[116:117], v[130:131], v[116:117] op_sel_hi:[0,1]
	v_pk_mul_f32 v[118:119], v[130:131], v[118:119] op_sel_hi:[0,1]
	v_pk_mul_f32 v[120:121], v[130:131], v[120:121] op_sel_hi:[0,1]
	v_pk_mul_f32 v[122:123], v[130:131], v[122:123] op_sel_hi:[0,1]
	v_pk_mul_f32 v[124:125], v[130:131], v[124:125] op_sel_hi:[0,1]
	v_pk_mul_f32 v[126:127], v[130:131], v[126:127] op_sel_hi:[0,1]
	v_pk_mul_f32 v[112:113], v[112:113], v[192:193]
	v_pk_mul_f32 v[114:115], v[114:115], v[194:195]
	v_pk_mul_f32 v[116:117], v[116:117], v[196:197]
	v_pk_mul_f32 v[118:119], v[118:119], v[198:199]
	v_pk_mul_f32 v[120:121], v[120:121], v[200:201]
	v_pk_mul_f32 v[122:123], v[122:123], v[202:203]
	v_pk_mul_f32 v[124:125], v[124:125], v[204:205]
	v_pk_mul_f32 v[126:127], v[126:127], v[206:207]
	v_lshlrev_b32_e32 v64, 16, v80
	v_and_b32_e32 v65, 0xffff0000, v80
	v_lshlrev_b32_e32 v66, 16, v81
	v_and_b32_e32 v67, 0xffff0000, v81
	v_lshlrev_b32_e32 v68, 16, v82
	v_and_b32_e32 v69, 0xffff0000, v82
	v_lshlrev_b32_e32 v70, 16, v83
	v_and_b32_e32 v71, 0xffff0000, v83
	v_pk_fma_f32 v[112:113], v[90:91], v[64:65], v[112:113] op_sel_hi:[0,1,1]
	v_pk_fma_f32 v[114:115], v[90:91], v[66:67], v[114:115] op_sel_hi:[0,1,1]
	v_pk_fma_f32 v[116:117], v[90:91], v[68:69], v[116:117] op_sel_hi:[0,1,1]
	v_pk_fma_f32 v[118:119], v[90:91], v[70:71], v[118:119] op_sel_hi:[0,1,1]
	v_lshlrev_b32_e32 v64, 16, v84
	v_and_b32_e32 v65, 0xffff0000, v84
	v_lshlrev_b32_e32 v66, 16, v85
	v_and_b32_e32 v67, 0xffff0000, v85
	v_lshlrev_b32_e32 v68, 16, v86
	v_and_b32_e32 v69, 0xffff0000, v86
	v_lshlrev_b32_e32 v70, 16, v87
	v_and_b32_e32 v71, 0xffff0000, v87
	v_pk_fma_f32 v[120:121], v[90:91], v[64:65], v[120:121] op_sel_hi:[0,1,1]
	v_pk_fma_f32 v[122:123], v[90:91], v[66:67], v[122:123] op_sel_hi:[0,1,1]
	v_pk_fma_f32 v[124:125], v[90:91], v[68:69], v[124:125] op_sel_hi:[0,1,1]
	v_pk_fma_f32 v[126:127], v[90:91], v[70:71], v[126:127] op_sel_hi:[0,1,1]
	global_store_dwordx4 v175, v[112:115], s[100:101]
	global_store_dwordx4 v175, v[116:119], s[100:101] offset:1024
	global_store_dwordx4 v175, v[120:123], s[100:101] offset:2048
	global_store_dwordx4 v175, v[124:127], s[100:101] offset:3072
	v_add_u32_e32 v175, 0x800000, v175
	s_waitcnt vmcnt(12)
;     __device__ __forceinline__ const float* in(int i) const { return karg_in(i); }
;     __device__ __forceinline__ float* out() const { return (float*)karg_in(33); }
; __device__ __forceinline__ float ssq4(v4f v) { return (v.x * v.x + v.y * v.y) + (v.z * v.z + v.w * v.w); }
; #define FTID const int ftid_ = fresh_tid()
; template <int R, bool BASE_F32, bool OUT_F32>
; __device__ __forceinline__ void rows_res(const Ctx& C, int m0, int stride, int mx, const float* gpost, float scale, int lane) {
;     ...
;     for (int r = 0; r < R; ++r) { float s = 0.f;
; #pragma unroll
;         for (int j = 0; j < 4; ++j) s += ssq4(d[r][j]);
;         r1[r] = s; }
; #pragma unroll
;     for (int r = 0; r < R; ++r) r1[r] = rsqrtf(wave_sum(r1[r]) * (1.f / DM) + EPS) * scale;
; #pragma unroll
;     for (int j = 0; j < 4; ++j) { const v4f gp = ld4_f32(gpost + 4 * lane + 256 * j);
; #pragma unroll
;         for (int r = 0; r < R; ++r) d[r][j] = b[r][j] + d[r][j] * r1[r] * gp; }
;     if (OUT_F32) { float* Y = C.out();
; #pragma unroll
;         for (int r = 0; r < R; ++r)
; #pragma unroll
;             for (int j = 0; j < 4; ++j) if (ok[r]) *(v4f*)(Y + (size_t)mr[r] * DM + 4 * lane + 256 * j) = d[r][j];
; __global__ void __launch_bounds__(NTHREADS, 2) fwd_kernel(Args args) {
;     ...
;     { FTID; const float* gp = C.in(32); { const int gw_ = GWV, ngw_ = NGWV, nit = (MPROMPT + 4 * ngw_ - 1) / (4 * ngw_);
;       for (int it = 0; it < nit - 1; ++it) rows_res<4, false, true>(C, gw_ + 4 * it * ngw_, ngw_, M, gp, 0.5f, LANE);
;       rows_res<5, false, true>(C, gw_ + 4 * (nit - 1) * ngw_, ngw_, MPROMPT + gw_, gp, 0.5f, LANE);
;       for (int ms = MPROMPT + gw_ + ngw_; ms < M; ms += ngw_) rows_res<5, false, true>(C, MPROMPT, ngw_, ms, gp, 0.5f, LANE); } }
	v_lshlrev_b32_e32 v96, 16, v20
	v_and_b32_e32 v97, 0xffff0000, v20
	v_lshlrev_b32_e32 v98, 16, v21
	v_and_b32_e32 v99, 0xffff0000, v21
	v_lshlrev_b32_e32 v100, 16, v22
	v_and_b32_e32 v101, 0xffff0000, v22
	v_lshlrev_b32_e32 v102, 16, v23
	v_and_b32_e32 v103, 0xffff0000, v23
	v_lshlrev_b32_e32 v104, 16, v24
	v_and_b32_e32 v105, 0xffff0000, v24
	v_lshlrev_b32_e32 v106, 16, v25
	v_and_b32_e32 v107, 0xffff0000, v25
	v_lshlrev_b32_e32 v108, 16, v26
	v_and_b32_e32 v109, 0xffff0000, v26
	v_lshlrev_b32_e32 v110, 16, v27
	v_and_b32_e32 v111, 0xffff0000, v27
	v_pk_mul_f32 v[128:129], v[96:97], v[96:97]
	v_pk_fma_f32 v[128:129], v[98:99], v[98:99], v[128:129]
	v_pk_fma_f32 v[128:129], v[100:101], v[100:101], v[128:129]
	v_pk_fma_f32 v[128:129], v[102:103], v[102:103], v[128:129]
	v_pk_fma_f32 v[128:129], v[104:105], v[104:105], v[128:129]
	v_pk_fma_f32 v[128:129], v[106:107], v[106:107], v[128:129]
	v_pk_fma_f32 v[128:129], v[108:109], v[108:109], v[128:129]
	v_pk_fma_f32 v[128:129], v[110:111], v[110:111], v[128:129]
	s_nop 0
	v_add_f32_e32 v128, v128, v129
	s_nop 1
	v_add_f32_dpp v128, v128, v128 quad_perm:[1,0,3,2] row_mask:0xf bank_mask:0xf
	s_nop 1
	v_add_f32_dpp v128, v128, v128 quad_perm:[2,3,0,1] row_mask:0xf bank_mask:0xf
	s_nop 1
	v_add_f32_dpp v128, v128, v128 row_half_mirror row_mask:0xf bank_mask:0xf
	s_nop 1
	v_add_f32_dpp v128, v128, v128 row_mirror row_mask:0xf bank_mask:0xf
	s_nop 1
	ds_bpermute_b32 v136, v187, v128
	s_waitcnt lgkmcnt(0)
	v_add_f32_e32 v128, v128, v136
	ds_bpermute_b32 v136, v188, v128
	s_waitcnt lgkmcnt(0)
	v_add_f32_e32 v128, v128, v136
	v_fmamk_f32 v128, v128, 0x3a800000, v138
	s_nop 0
	v_rsq_f32_e32 v128, v128
	s_nop 1
	v_mul_f32_e32 v128, 0.5, v128
	s_waitcnt vmcnt(8)
	v_pk_mul_f32 v[96:97], v[128:129], v[96:97] op_sel_hi:[0,1]
	v_pk_mul_f32 v[98:99], v[128:129], v[98:99] op_sel_hi:[0,1]
	v_pk_mul_f32 v[100:101], v[128:129], v[100:101] op_sel_hi:[0,1]
	v_pk_mul_f32 v[102:103], v[128:129], v[102:103] op_sel_hi:[0,1]
	v_pk_mul_f32 v[104:105], v[128:129], v[104:105] op_sel_hi:[0,1]
	v_pk_mul_f32 v[106:107], v[128:129], v[106:107] op_sel_hi:[0,1]
	v_pk_mul_f32 v[108:109], v[128:129], v[108:109] op_sel_hi:[0,1]
	v_pk_mul_f32 v[110:111], v[128:129], v[110:111] op_sel_hi:[0,1]
	v_pk_mul_f32 v[96:97], v[96:97], v[192:193]
	v_pk_mul_f32 v[98:99], v[98:99], v[194:195]
	v_pk_mul_f32 v[100:101], v[100:101], v[196:197]
	v_pk_mul_f32 v[102:103], v[102:103], v[198:199]
	v_pk_mul_f32 v[104:105], v[104:105], v[200:201]
	v_pk_mul_f32 v[106:107], v[106:107], v[202:203]
	v_pk_mul_f32 v[108:109], v[108:109], v[204:205]
	v_pk_mul_f32 v[110:111], v[110:111], v[206:207]
	v_lshlrev_b32_e32 v20, 16, v36
	v_and_b32_e32 v21, 0xffff0000, v36
	v_lshlrev_b32_e32 v22, 16, v37
	v_and_b32_e32 v23, 0xffff0000, v37
	v_lshlrev_b32_e32 v24, 16, v38
	v_and_b32_e32 v25, 0xffff0000, v38
	v_lshlrev_b32_e32 v26, 16, v39
	v_and_b32_e32 v27, 0xffff0000, v39
	v_pk_fma_f32 v[96:97], v[52:53], v[20:21], v[96:97] op_sel_hi:[0,1,1]
	v_pk_fma_f32 v[98:99], v[52:53], v[22:23], v[98:99] op_sel_hi:[0,1,1]
	v_pk_fma_f32 v[100:101], v[52:53], v[24:25], v[100:101] op_sel_hi:[0,1,1]
	v_pk_fma_f32 v[102:103], v[52:53], v[26:27], v[102:103] op_sel_hi:[0,1,1]
	v_lshlrev_b32_e32 v20, 16, v40
	v_and_b32_e32 v21, 0xffff0000, v40
	v_lshlrev_b32_e32 v22, 16, v41
	v_and_b32_e32 v23, 0xffff0000, v41
	v_lshlrev_b32_e32 v24, 16, v42
	v_and_b32_e32 v25, 0xffff0000, v42
	v_lshlrev_b32_e32 v26, 16, v43
	v_and_b32_e32 v27, 0xffff0000, v43
	v_pk_fma_f32 v[104:105], v[52:53], v[20:21], v[104:105] op_sel_hi:[0,1,1]
	v_pk_fma_f32 v[106:107], v[52:53], v[22:23], v[106:107] op_sel_hi:[0,1,1]
	v_pk_fma_f32 v[108:109], v[52:53], v[24:25], v[108:109] op_sel_hi:[0,1,1]
	v_pk_fma_f32 v[110:111], v[52:53], v[26:27], v[110:111] op_sel_hi:[0,1,1]
	s_cmpk_lt_i32 s15, 0x80
	s_cbranch_scc0 .LLEAN13_NOSAMPLE
	global_store_dwordx4 v175, v[96:99], s[100:101]
	global_store_dwordx4 v175, v[100:103], s[100:101] offset:1024
	global_store_dwordx4 v175, v[104:107], s[100:101] offset:2048
	global_store_dwordx4 v175, v[108:111], s[100:101] offset:3072
	v_add_u32_e32 v175, 0x800000, v175
.LLEAN13_NOSAMPLE:
	s_endpgm
	s_waitcnt lgkmcnt(0)
	v_lshl_add_u64 v[20:21], s[8:9], 0, v[16:17]
	v_mov_b32_e32 v19, v17
	s_mov_b64 s[10:11], 0x7100000
	s_mov_b64 s[12:13], 0x3000000
	v_mov_b32_e32 v23, 0x2a80000
	v_mov_b32_e32 v22, 0x358637bd
	s_mov_b32 s14, 0x3a800000
	s_mov_b32 s27, 0x800000
	s_mov_b32 s16, s15
	s_branch .LBB0_1275
